# skinny GEMMs (128 sample rows): loads cover 8 rows x 128 B (full cache lines) with a DPP row-half swap into MFMA fragment layout, instead of 16 rows x 64 B
# baseline (speedup 1.0000x reference)
.LBB0_1040:
	v_mov_b32_e32 v64, v183
	s_and_b32 s19, s4, 64
	v_and_b32_e32 v63, 15, v64
	v_or_b32_e32 v0, s19, v63
	v_readfirstlane_b32 s2, v64
	v_mul_u32_u24_e32 v0, 0x1600, v0
	v_readlane_b32 s20, v233, 8
	s_ashr_i32 s3, s2, 6
	v_lshlrev_b32_e32 v48, 1, v0
	v_readlane_b32 s21, v233, 9
	v_bfi_b32 v2, 15, v64, s9
	s_movk_i32 s22, 0x2c00
	s_waitcnt lgkmcnt(0)
	v_lshl_add_u64 v[0:1], s[20:21], 0, v[48:49]
	s_mul_i32 s20, s3, 0x2c0
	s_ashr_i32 s21, s20, 31
	s_lshl_b64 s[20:21], s[20:21], 1
	v_mad_i64_i32 v[2:3], s[22:23], v2, s22, v[50:51]
	v_lshl_add_u64 v[0:1], v[0:1], 0, s[20:21]
	v_and_b32_e32 v48, 48, v64
	v_lshl_add_u64 v[2:3], v[2:3], 0, s[20:21]
	v_lshl_add_u64 v[8:9], v[0:1], 0, v[48:49]
	v_lshl_add_u64 v[58:59], v[2:3], 0, v[48:49]
	s_lshl_b32 s20, s3, 12
	v_and_b32_e32 v2, 63, v64
	v_lshrrev_b32_e32 v196, 3, v63
	v_mul_u32_u24_e32 v196, 0x15fc0, v196
	v_sub_u32_e32 v194, 0, v196
	v_ashrrev_i32_e32 v195, 31, v194
	s_mov_b32 s101, 0
	v_lshl_add_u64 v[170:171], v[58:59], 0, v[194:195]
	s_mov_b32 s100, 0x16000
	v_lshl_add_u64 v[172:173], v[170:171], 0, s[100:101]
	v_lshl_add_u64 v[166:167], v[8:9], 0, v[194:195]
	s_mov_b32 s100, 0x5800000
	v_lshl_add_u64 v[174:175], v[166:167], 0, s[100:101]
	s_mov_b32 s100, 0x5816000
	v_lshl_add_u64 v[176:177], v[166:167], 0, s[100:101]
	s_mov_b32 s100, 0x582c000
	v_lshl_add_u64 v[178:179], v[166:167], 0, s[100:101]
	s_mov_b32 s100, 0x5842000
	v_lshl_add_u64 v[180:181], v[166:167], 0, s[100:101]
	s_mov_b32 s100, 0x5858000
	v_lshl_add_u64 v[184:185], v[166:167], 0, s[100:101]
	s_mov_b32 s100, 0x586e000
	v_lshl_add_u64 v[186:187], v[166:167], 0, s[100:101]
	s_mov_b32 s100, 0x5884000
	v_lshl_add_u64 v[190:191], v[166:167], 0, s[100:101]
	s_mov_b32 s100, 0x589a000
	v_lshl_add_u64 v[192:193], v[166:167], 0, s[100:101]
	global_load_dwordx4 v[84:87], v[170:171], off
	global_load_dwordx4 v[88:91], v[172:173], off
	global_load_dwordx4 v[92:95], v[174:175], off
	global_load_dwordx4 v[96:99], v[176:177], off
	global_load_dwordx4 v[100:103], v[178:179], off
	global_load_dwordx4 v[104:107], v[180:181], off
	global_load_dwordx4 v[108:111], v[184:185], off
	global_load_dwordx4 v[112:115], v[186:187], off
	global_load_dwordx4 v[116:119], v[190:191], off
	global_load_dwordx4 v[120:123], v[192:193], off
	global_load_dwordx4 v[124:127], v[170:171], off offset:128
	global_load_dwordx4 v[128:131], v[172:173], off offset:128
	global_load_dwordx4 v[132:135], v[174:175], off offset:128
	global_load_dwordx4 v[136:139], v[176:177], off offset:128
	global_load_dwordx4 v[140:143], v[178:179], off offset:128
	global_load_dwordx4 v[146:149], v[180:181], off offset:128
	global_load_dwordx4 v[150:153], v[184:185], off offset:128
	global_load_dwordx4 v[154:157], v[186:187], off offset:128
	global_load_dwordx4 v[158:161], v[190:191], off offset:128
	global_load_dwordx4 v[162:165], v[192:193], off offset:128
	s_waitcnt vmcnt(10)
	v_mov_b32_e32 v166, v88
	v_mov_b32_e32 v167, v89
	v_mov_b32_e32 v168, v90
	v_mov_b32_e32 v169, v91
	v_mov_b32_dpp v88, v84 row_shl:8 row_mask:0xf bank_mask:0x3
	v_mov_b32_dpp v89, v85 row_shl:8 row_mask:0xf bank_mask:0x3
	v_mov_b32_dpp v90, v86 row_shl:8 row_mask:0xf bank_mask:0x3
	v_mov_b32_dpp v91, v87 row_shl:8 row_mask:0xf bank_mask:0x3
	v_mov_b32_dpp v84, v166 row_shr:8 row_mask:0xf bank_mask:0xc
	v_mov_b32_dpp v85, v167 row_shr:8 row_mask:0xf bank_mask:0xc
	v_mov_b32_dpp v86, v168 row_shr:8 row_mask:0xf bank_mask:0xc
	v_mov_b32_dpp v87, v169 row_shr:8 row_mask:0xf bank_mask:0xc
	v_mov_b32_e32 v166, v96
	v_mov_b32_e32 v167, v97
	v_mov_b32_e32 v168, v98
	v_mov_b32_e32 v169, v99
	v_mov_b32_dpp v96, v92 row_shl:8 row_mask:0xf bank_mask:0x3
	v_mov_b32_dpp v97, v93 row_shl:8 row_mask:0xf bank_mask:0x3
	v_mov_b32_dpp v98, v94 row_shl:8 row_mask:0xf bank_mask:0x3
	v_mov_b32_dpp v99, v95 row_shl:8 row_mask:0xf bank_mask:0x3
	v_mov_b32_dpp v92, v166 row_shr:8 row_mask:0xf bank_mask:0xc
	v_mov_b32_dpp v93, v167 row_shr:8 row_mask:0xf bank_mask:0xc
	v_mov_b32_dpp v94, v168 row_shr:8 row_mask:0xf bank_mask:0xc
	v_mov_b32_dpp v95, v169 row_shr:8 row_mask:0xf bank_mask:0xc
	v_mov_b32_e32 v166, v104
	v_mov_b32_e32 v167, v105
	v_mov_b32_e32 v168, v106
	v_mov_b32_e32 v169, v107
	v_mov_b32_dpp v104, v100 row_shl:8 row_mask:0xf bank_mask:0x3
	v_mov_b32_dpp v105, v101 row_shl:8 row_mask:0xf bank_mask:0x3
	v_mov_b32_dpp v106, v102 row_shl:8 row_mask:0xf bank_mask:0x3
	v_mov_b32_dpp v107, v103 row_shl:8 row_mask:0xf bank_mask:0x3
	v_mov_b32_dpp v100, v166 row_shr:8 row_mask:0xf bank_mask:0xc
	v_mov_b32_dpp v101, v167 row_shr:8 row_mask:0xf bank_mask:0xc
	v_mov_b32_dpp v102, v168 row_shr:8 row_mask:0xf bank_mask:0xc
	v_mov_b32_dpp v103, v169 row_shr:8 row_mask:0xf bank_mask:0xc
	v_mov_b32_e32 v166, v112
	v_mov_b32_e32 v167, v113
	v_mov_b32_e32 v168, v114
	v_mov_b32_e32 v169, v115
	v_mov_b32_dpp v112, v108 row_shl:8 row_mask:0xf bank_mask:0x3
	v_mov_b32_dpp v113, v109 row_shl:8 row_mask:0xf bank_mask:0x3
	v_mov_b32_dpp v114, v110 row_shl:8 row_mask:0xf bank_mask:0x3
	v_mov_b32_dpp v115, v111 row_shl:8 row_mask:0xf bank_mask:0x3
	v_mov_b32_dpp v108, v166 row_shr:8 row_mask:0xf bank_mask:0xc
	v_mov_b32_dpp v109, v167 row_shr:8 row_mask:0xf bank_mask:0xc
	v_mov_b32_dpp v110, v168 row_shr:8 row_mask:0xf bank_mask:0xc
	v_mov_b32_dpp v111, v169 row_shr:8 row_mask:0xf bank_mask:0xc
	v_mov_b32_e32 v166, v120
	v_mov_b32_e32 v167, v121
	v_mov_b32_e32 v168, v122
	v_mov_b32_e32 v169, v123
	v_mov_b32_dpp v120, v116 row_shl:8 row_mask:0xf bank_mask:0x3
	v_mov_b32_dpp v121, v117 row_shl:8 row_mask:0xf bank_mask:0x3
	v_mov_b32_dpp v122, v118 row_shl:8 row_mask:0xf bank_mask:0x3
	v_mov_b32_dpp v123, v119 row_shl:8 row_mask:0xf bank_mask:0x3
	v_mov_b32_dpp v116, v166 row_shr:8 row_mask:0xf bank_mask:0xc
	v_mov_b32_dpp v117, v167 row_shr:8 row_mask:0xf bank_mask:0xc
	v_mov_b32_dpp v118, v168 row_shr:8 row_mask:0xf bank_mask:0xc
	v_mov_b32_dpp v119, v169 row_shr:8 row_mask:0xf bank_mask:0xc
	v_mfma_f32_16x16x32_bf16 v[198:201], v[84:87], v[92:95], 0
	v_mfma_f32_16x16x32_bf16 v[202:205], v[84:87], v[100:103], 0
	v_mfma_f32_16x16x32_bf16 v[206:209], v[84:87], v[108:111], 0
	v_mfma_f32_16x16x32_bf16 v[210:213], v[84:87], v[116:119], 0
	v_mfma_f32_16x16x32_bf16 v[198:201], v[88:91], v[96:99], v[198:201]
	v_mfma_f32_16x16x32_bf16 v[202:205], v[88:91], v[104:107], v[202:205]
	v_mfma_f32_16x16x32_bf16 v[206:209], v[88:91], v[112:115], v[206:209]
	v_mfma_f32_16x16x32_bf16 v[210:213], v[88:91], v[120:123], v[210:213]
	global_load_dwordx4 v[84:87], v[170:171], off offset:256
	global_load_dwordx4 v[88:91], v[172:173], off offset:256
	global_load_dwordx4 v[92:95], v[174:175], off offset:256
	global_load_dwordx4 v[96:99], v[176:177], off offset:256
	global_load_dwordx4 v[100:103], v[178:179], off offset:256
	global_load_dwordx4 v[104:107], v[180:181], off offset:256
	global_load_dwordx4 v[108:111], v[184:185], off offset:256
	global_load_dwordx4 v[112:115], v[186:187], off offset:256
	global_load_dwordx4 v[116:119], v[190:191], off offset:256
	global_load_dwordx4 v[120:123], v[192:193], off offset:256
	s_waitcnt vmcnt(10)
	v_mov_b32_e32 v166, v128
	v_mov_b32_e32 v167, v129
	v_mov_b32_e32 v168, v130
	v_mov_b32_e32 v169, v131
	v_mov_b32_dpp v128, v124 row_shl:8 row_mask:0xf bank_mask:0x3
	v_mov_b32_dpp v129, v125 row_shl:8 row_mask:0xf bank_mask:0x3
	v_mov_b32_dpp v130, v126 row_shl:8 row_mask:0xf bank_mask:0x3
	v_mov_b32_dpp v131, v127 row_shl:8 row_mask:0xf bank_mask:0x3
	v_mov_b32_dpp v124, v166 row_shr:8 row_mask:0xf bank_mask:0xc
	v_mov_b32_dpp v125, v167 row_shr:8 row_mask:0xf bank_mask:0xc
	v_mov_b32_dpp v126, v168 row_shr:8 row_mask:0xf bank_mask:0xc
	v_mov_b32_dpp v127, v169 row_shr:8 row_mask:0xf bank_mask:0xc
	v_mov_b32_e32 v166, v136
	v_mov_b32_e32 v167, v137
	v_mov_b32_e32 v168, v138
	v_mov_b32_e32 v169, v139
	v_mov_b32_dpp v136, v132 row_shl:8 row_mask:0xf bank_mask:0x3
	v_mov_b32_dpp v137, v133 row_shl:8 row_mask:0xf bank_mask:0x3
	v_mov_b32_dpp v138, v134 row_shl:8 row_mask:0xf bank_mask:0x3
	v_mov_b32_dpp v139, v135 row_shl:8 row_mask:0xf bank_mask:0x3
	v_mov_b32_dpp v132, v166 row_shr:8 row_mask:0xf bank_mask:0xc
	v_mov_b32_dpp v133, v167 row_shr:8 row_mask:0xf bank_mask:0xc
	v_mov_b32_dpp v134, v168 row_shr:8 row_mask:0xf bank_mask:0xc
	v_mov_b32_dpp v135, v169 row_shr:8 row_mask:0xf bank_mask:0xc
	v_mov_b32_e32 v166, v146
	v_mov_b32_e32 v167, v147
	v_mov_b32_e32 v168, v148
	v_mov_b32_e32 v169, v149
	v_mov_b32_dpp v146, v140 row_shl:8 row_mask:0xf bank_mask:0x3
	v_mov_b32_dpp v147, v141 row_shl:8 row_mask:0xf bank_mask:0x3
	v_mov_b32_dpp v148, v142 row_shl:8 row_mask:0xf bank_mask:0x3
	v_mov_b32_dpp v149, v143 row_shl:8 row_mask:0xf bank_mask:0x3
	v_mov_b32_dpp v140, v166 row_shr:8 row_mask:0xf bank_mask:0xc
	v_mov_b32_dpp v141, v167 row_shr:8 row_mask:0xf bank_mask:0xc
	v_mov_b32_dpp v142, v168 row_shr:8 row_mask:0xf bank_mask:0xc
	v_mov_b32_dpp v143, v169 row_shr:8 row_mask:0xf bank_mask:0xc
	v_mov_b32_e32 v166, v154
	v_mov_b32_e32 v167, v155
	v_mov_b32_e32 v168, v156
	v_mov_b32_e32 v169, v157
	v_mov_b32_dpp v154, v150 row_shl:8 row_mask:0xf bank_mask:0x3
	v_mov_b32_dpp v155, v151 row_shl:8 row_mask:0xf bank_mask:0x3
	v_mov_b32_dpp v156, v152 row_shl:8 row_mask:0xf bank_mask:0x3
	v_mov_b32_dpp v157, v153 row_shl:8 row_mask:0xf bank_mask:0x3
	v_mov_b32_dpp v150, v166 row_shr:8 row_mask:0xf bank_mask:0xc
	v_mov_b32_dpp v151, v167 row_shr:8 row_mask:0xf bank_mask:0xc
	v_mov_b32_dpp v152, v168 row_shr:8 row_mask:0xf bank_mask:0xc
	v_mov_b32_dpp v153, v169 row_shr:8 row_mask:0xf bank_mask:0xc
	v_mov_b32_e32 v166, v162
	v_mov_b32_e32 v167, v163
	v_mov_b32_e32 v168, v164
	v_mov_b32_e32 v169, v165
	v_mov_b32_dpp v162, v158 row_shl:8 row_mask:0xf bank_mask:0x3
	v_mov_b32_dpp v163, v159 row_shl:8 row_mask:0xf bank_mask:0x3
	v_mov_b32_dpp v164, v160 row_shl:8 row_mask:0xf bank_mask:0x3
	v_mov_b32_dpp v165, v161 row_shl:8 row_mask:0xf bank_mask:0x3
	v_mov_b32_dpp v158, v166 row_shr:8 row_mask:0xf bank_mask:0xc
	v_mov_b32_dpp v159, v167 row_shr:8 row_mask:0xf bank_mask:0xc
	v_mov_b32_dpp v160, v168 row_shr:8 row_mask:0xf bank_mask:0xc
	v_mov_b32_dpp v161, v169 row_shr:8 row_mask:0xf bank_mask:0xc
	v_mfma_f32_16x16x32_bf16 v[198:201], v[124:127], v[132:135], v[198:201]
	v_mfma_f32_16x16x32_bf16 v[202:205], v[124:127], v[140:143], v[202:205]
	v_mfma_f32_16x16x32_bf16 v[206:209], v[124:127], v[150:153], v[206:209]
	v_mfma_f32_16x16x32_bf16 v[210:213], v[124:127], v[158:161], v[210:213]
	v_mfma_f32_16x16x32_bf16 v[198:201], v[128:131], v[136:139], v[198:201]
	v_mfma_f32_16x16x32_bf16 v[202:205], v[128:131], v[146:149], v[202:205]
	v_mfma_f32_16x16x32_bf16 v[206:209], v[128:131], v[154:157], v[206:209]
	v_mfma_f32_16x16x32_bf16 v[210:213], v[128:131], v[162:165], v[210:213]
	global_load_dwordx4 v[124:127], v[170:171], off offset:384
	global_load_dwordx4 v[128:131], v[172:173], off offset:384
	global_load_dwordx4 v[132:135], v[174:175], off offset:384
	global_load_dwordx4 v[136:139], v[176:177], off offset:384
	global_load_dwordx4 v[140:143], v[178:179], off offset:384
	global_load_dwordx4 v[146:149], v[180:181], off offset:384
	global_load_dwordx4 v[150:153], v[184:185], off offset:384
	global_load_dwordx4 v[154:157], v[186:187], off offset:384
	global_load_dwordx4 v[158:161], v[190:191], off offset:384
	global_load_dwordx4 v[162:165], v[192:193], off offset:384
	s_waitcnt vmcnt(10)
	v_mov_b32_e32 v166, v88
	v_mov_b32_e32 v167, v89
	v_mov_b32_e32 v168, v90
	v_mov_b32_e32 v169, v91
	v_mov_b32_dpp v88, v84 row_shl:8 row_mask:0xf bank_mask:0x3
	v_mov_b32_dpp v89, v85 row_shl:8 row_mask:0xf bank_mask:0x3
	v_mov_b32_dpp v90, v86 row_shl:8 row_mask:0xf bank_mask:0x3
	v_mov_b32_dpp v91, v87 row_shl:8 row_mask:0xf bank_mask:0x3
	v_mov_b32_dpp v84, v166 row_shr:8 row_mask:0xf bank_mask:0xc
	v_mov_b32_dpp v85, v167 row_shr:8 row_mask:0xf bank_mask:0xc
	v_mov_b32_dpp v86, v168 row_shr:8 row_mask:0xf bank_mask:0xc
	v_mov_b32_dpp v87, v169 row_shr:8 row_mask:0xf bank_mask:0xc
	v_mov_b32_e32 v166, v96
	v_mov_b32_e32 v167, v97
	v_mov_b32_e32 v168, v98
	v_mov_b32_e32 v169, v99
	v_mov_b32_dpp v96, v92 row_shl:8 row_mask:0xf bank_mask:0x3
	v_mov_b32_dpp v97, v93 row_shl:8 row_mask:0xf bank_mask:0x3
	v_mov_b32_dpp v98, v94 row_shl:8 row_mask:0xf bank_mask:0x3
	v_mov_b32_dpp v99, v95 row_shl:8 row_mask:0xf bank_mask:0x3
	v_mov_b32_dpp v92, v166 row_shr:8 row_mask:0xf bank_mask:0xc
	v_mov_b32_dpp v93, v167 row_shr:8 row_mask:0xf bank_mask:0xc
	v_mov_b32_dpp v94, v168 row_shr:8 row_mask:0xf bank_mask:0xc
	v_mov_b32_dpp v95, v169 row_shr:8 row_mask:0xf bank_mask:0xc
	v_mov_b32_e32 v166, v104
	v_mov_b32_e32 v167, v105
	v_mov_b32_e32 v168, v106
	v_mov_b32_e32 v169, v107
	v_mov_b32_dpp v104, v100 row_shl:8 row_mask:0xf bank_mask:0x3
	v_mov_b32_dpp v105, v101 row_shl:8 row_mask:0xf bank_mask:0x3
	v_mov_b32_dpp v106, v102 row_shl:8 row_mask:0xf bank_mask:0x3
	v_mov_b32_dpp v107, v103 row_shl:8 row_mask:0xf bank_mask:0x3
	v_mov_b32_dpp v100, v166 row_shr:8 row_mask:0xf bank_mask:0xc
	v_mov_b32_dpp v101, v167 row_shr:8 row_mask:0xf bank_mask:0xc
	v_mov_b32_dpp v102, v168 row_shr:8 row_mask:0xf bank_mask:0xc
	v_mov_b32_dpp v103, v169 row_shr:8 row_mask:0xf bank_mask:0xc
	v_mov_b32_e32 v166, v112
	v_mov_b32_e32 v167, v113
	v_mov_b32_e32 v168, v114
	v_mov_b32_e32 v169, v115
	v_mov_b32_dpp v112, v108 row_shl:8 row_mask:0xf bank_mask:0x3
	v_mov_b32_dpp v113, v109 row_shl:8 row_mask:0xf bank_mask:0x3
	v_mov_b32_dpp v114, v110 row_shl:8 row_mask:0xf bank_mask:0x3
	v_mov_b32_dpp v115, v111 row_shl:8 row_mask:0xf bank_mask:0x3
	v_mov_b32_dpp v108, v166 row_shr:8 row_mask:0xf bank_mask:0xc
	v_mov_b32_dpp v109, v167 row_shr:8 row_mask:0xf bank_mask:0xc
	v_mov_b32_dpp v110, v168 row_shr:8 row_mask:0xf bank_mask:0xc
	v_mov_b32_dpp v111, v169 row_shr:8 row_mask:0xf bank_mask:0xc
	v_mov_b32_e32 v166, v120
	v_mov_b32_e32 v167, v121
	v_mov_b32_e32 v168, v122
	v_mov_b32_e32 v169, v123
	v_mov_b32_dpp v120, v116 row_shl:8 row_mask:0xf bank_mask:0x3
	v_mov_b32_dpp v121, v117 row_shl:8 row_mask:0xf bank_mask:0x3
	v_mov_b32_dpp v122, v118 row_shl:8 row_mask:0xf bank_mask:0x3
	v_mov_b32_dpp v123, v119 row_shl:8 row_mask:0xf bank_mask:0x3
	v_mov_b32_dpp v116, v166 row_shr:8 row_mask:0xf bank_mask:0xc
	v_mov_b32_dpp v117, v167 row_shr:8 row_mask:0xf bank_mask:0xc
	v_mov_b32_dpp v118, v168 row_shr:8 row_mask:0xf bank_mask:0xc
	v_mov_b32_dpp v119, v169 row_shr:8 row_mask:0xf bank_mask:0xc
	v_mfma_f32_16x16x32_bf16 v[198:201], v[84:87], v[92:95], v[198:201]
	v_mfma_f32_16x16x32_bf16 v[202:205], v[84:87], v[100:103], v[202:205]
	v_mfma_f32_16x16x32_bf16 v[206:209], v[84:87], v[108:111], v[206:209]
	v_mfma_f32_16x16x32_bf16 v[210:213], v[84:87], v[116:119], v[210:213]
	v_mfma_f32_16x16x32_bf16 v[198:201], v[88:91], v[96:99], v[198:201]
	v_mfma_f32_16x16x32_bf16 v[202:205], v[88:91], v[104:107], v[202:205]
	v_mfma_f32_16x16x32_bf16 v[206:209], v[88:91], v[112:115], v[206:209]
	v_mfma_f32_16x16x32_bf16 v[210:213], v[88:91], v[120:123], v[210:213]
	global_load_dwordx4 v[84:87], v[170:171], off offset:512
	global_load_dwordx4 v[88:91], v[172:173], off offset:512
	global_load_dwordx4 v[92:95], v[174:175], off offset:512
	global_load_dwordx4 v[96:99], v[176:177], off offset:512
	global_load_dwordx4 v[100:103], v[178:179], off offset:512
	global_load_dwordx4 v[104:107], v[180:181], off offset:512
	global_load_dwordx4 v[108:111], v[184:185], off offset:512
	global_load_dwordx4 v[112:115], v[186:187], off offset:512
	global_load_dwordx4 v[116:119], v[190:191], off offset:512
	global_load_dwordx4 v[120:123], v[192:193], off offset:512
	s_waitcnt vmcnt(10)
	v_mov_b32_e32 v166, v128
	v_mov_b32_e32 v167, v129
	v_mov_b32_e32 v168, v130
	v_mov_b32_e32 v169, v131
	v_mov_b32_dpp v128, v124 row_shl:8 row_mask:0xf bank_mask:0x3
	v_mov_b32_dpp v129, v125 row_shl:8 row_mask:0xf bank_mask:0x3
	v_mov_b32_dpp v130, v126 row_shl:8 row_mask:0xf bank_mask:0x3
	v_mov_b32_dpp v131, v127 row_shl:8 row_mask:0xf bank_mask:0x3
	v_mov_b32_dpp v124, v166 row_shr:8 row_mask:0xf bank_mask:0xc
	v_mov_b32_dpp v125, v167 row_shr:8 row_mask:0xf bank_mask:0xc
	v_mov_b32_dpp v126, v168 row_shr:8 row_mask:0xf bank_mask:0xc
	v_mov_b32_dpp v127, v169 row_shr:8 row_mask:0xf bank_mask:0xc
	v_mov_b32_e32 v166, v136
	v_mov_b32_e32 v167, v137
	v_mov_b32_e32 v168, v138
	v_mov_b32_e32 v169, v139
	v_mov_b32_dpp v136, v132 row_shl:8 row_mask:0xf bank_mask:0x3
	v_mov_b32_dpp v137, v133 row_shl:8 row_mask:0xf bank_mask:0x3
	v_mov_b32_dpp v138, v134 row_shl:8 row_mask:0xf bank_mask:0x3
	v_mov_b32_dpp v139, v135 row_shl:8 row_mask:0xf bank_mask:0x3
	v_mov_b32_dpp v132, v166 row_shr:8 row_mask:0xf bank_mask:0xc
	v_mov_b32_dpp v133, v167 row_shr:8 row_mask:0xf bank_mask:0xc
	v_mov_b32_dpp v134, v168 row_shr:8 row_mask:0xf bank_mask:0xc
	v_mov_b32_dpp v135, v169 row_shr:8 row_mask:0xf bank_mask:0xc
	v_mov_b32_e32 v166, v146
	v_mov_b32_e32 v167, v147
	v_mov_b32_e32 v168, v148
	v_mov_b32_e32 v169, v149
	v_mov_b32_dpp v146, v140 row_shl:8 row_mask:0xf bank_mask:0x3
	v_mov_b32_dpp v147, v141 row_shl:8 row_mask:0xf bank_mask:0x3
	v_mov_b32_dpp v148, v142 row_shl:8 row_mask:0xf bank_mask:0x3
	v_mov_b32_dpp v149, v143 row_shl:8 row_mask:0xf bank_mask:0x3
	v_mov_b32_dpp v140, v166 row_shr:8 row_mask:0xf bank_mask:0xc
	v_mov_b32_dpp v141, v167 row_shr:8 row_mask:0xf bank_mask:0xc
	v_mov_b32_dpp v142, v168 row_shr:8 row_mask:0xf bank_mask:0xc
	v_mov_b32_dpp v143, v169 row_shr:8 row_mask:0xf bank_mask:0xc
	v_mov_b32_e32 v166, v154
	v_mov_b32_e32 v167, v155
	v_mov_b32_e32 v168, v156
	v_mov_b32_e32 v169, v157
	v_mov_b32_dpp v154, v150 row_shl:8 row_mask:0xf bank_mask:0x3
	v_mov_b32_dpp v155, v151 row_shl:8 row_mask:0xf bank_mask:0x3
	v_mov_b32_dpp v156, v152 row_shl:8 row_mask:0xf bank_mask:0x3
	v_mov_b32_dpp v157, v153 row_shl:8 row_mask:0xf bank_mask:0x3
	v_mov_b32_dpp v150, v166 row_shr:8 row_mask:0xf bank_mask:0xc
	v_mov_b32_dpp v151, v167 row_shr:8 row_mask:0xf bank_mask:0xc
	v_mov_b32_dpp v152, v168 row_shr:8 row_mask:0xf bank_mask:0xc
	v_mov_b32_dpp v153, v169 row_shr:8 row_mask:0xf bank_mask:0xc
	v_mov_b32_e32 v166, v162
	v_mov_b32_e32 v167, v163
	v_mov_b32_e32 v168, v164
	v_mov_b32_e32 v169, v165
	v_mov_b32_dpp v162, v158 row_shl:8 row_mask:0xf bank_mask:0x3
	v_mov_b32_dpp v163, v159 row_shl:8 row_mask:0xf bank_mask:0x3
	v_mov_b32_dpp v164, v160 row_shl:8 row_mask:0xf bank_mask:0x3
	v_mov_b32_dpp v165, v161 row_shl:8 row_mask:0xf bank_mask:0x3
	v_mov_b32_dpp v158, v166 row_shr:8 row_mask:0xf bank_mask:0xc
	v_mov_b32_dpp v159, v167 row_shr:8 row_mask:0xf bank_mask:0xc
	v_mov_b32_dpp v160, v168 row_shr:8 row_mask:0xf bank_mask:0xc
	v_mov_b32_dpp v161, v169 row_shr:8 row_mask:0xf bank_mask:0xc
	v_mfma_f32_16x16x32_bf16 v[198:201], v[124:127], v[132:135], v[198:201]
	v_mfma_f32_16x16x32_bf16 v[202:205], v[124:127], v[140:143], v[202:205]
	v_mfma_f32_16x16x32_bf16 v[206:209], v[124:127], v[150:153], v[206:209]
	v_mfma_f32_16x16x32_bf16 v[210:213], v[124:127], v[158:161], v[210:213]
	v_mfma_f32_16x16x32_bf16 v[198:201], v[128:131], v[136:139], v[198:201]
	v_mfma_f32_16x16x32_bf16 v[202:205], v[128:131], v[146:149], v[202:205]
	v_mfma_f32_16x16x32_bf16 v[206:209], v[128:131], v[154:157], v[206:209]
	v_mfma_f32_16x16x32_bf16 v[210:213], v[128:131], v[162:165], v[210:213]
	global_load_dwordx4 v[124:127], v[170:171], off offset:640
	global_load_dwordx4 v[128:131], v[172:173], off offset:640
	global_load_dwordx4 v[132:135], v[174:175], off offset:640
	global_load_dwordx4 v[136:139], v[176:177], off offset:640
	global_load_dwordx4 v[140:143], v[178:179], off offset:640
	global_load_dwordx4 v[146:149], v[180:181], off offset:640
	global_load_dwordx4 v[150:153], v[184:185], off offset:640
	global_load_dwordx4 v[154:157], v[186:187], off offset:640
	global_load_dwordx4 v[158:161], v[190:191], off offset:640
	global_load_dwordx4 v[162:165], v[192:193], off offset:640
	s_waitcnt vmcnt(10)
	v_mov_b32_e32 v166, v88
	v_mov_b32_e32 v167, v89
	v_mov_b32_e32 v168, v90
	v_mov_b32_e32 v169, v91
	v_mov_b32_dpp v88, v84 row_shl:8 row_mask:0xf bank_mask:0x3
	v_mov_b32_dpp v89, v85 row_shl:8 row_mask:0xf bank_mask:0x3
	v_mov_b32_dpp v90, v86 row_shl:8 row_mask:0xf bank_mask:0x3
	v_mov_b32_dpp v91, v87 row_shl:8 row_mask:0xf bank_mask:0x3
	v_mov_b32_dpp v84, v166 row_shr:8 row_mask:0xf bank_mask:0xc
	v_mov_b32_dpp v85, v167 row_shr:8 row_mask:0xf bank_mask:0xc
	v_mov_b32_dpp v86, v168 row_shr:8 row_mask:0xf bank_mask:0xc
	v_mov_b32_dpp v87, v169 row_shr:8 row_mask:0xf bank_mask:0xc
	v_mov_b32_e32 v166, v96
	v_mov_b32_e32 v167, v97
	v_mov_b32_e32 v168, v98
	v_mov_b32_e32 v169, v99
	v_mov_b32_dpp v96, v92 row_shl:8 row_mask:0xf bank_mask:0x3
	v_mov_b32_dpp v97, v93 row_shl:8 row_mask:0xf bank_mask:0x3
	v_mov_b32_dpp v98, v94 row_shl:8 row_mask:0xf bank_mask:0x3
	v_mov_b32_dpp v99, v95 row_shl:8 row_mask:0xf bank_mask:0x3
	v_mov_b32_dpp v92, v166 row_shr:8 row_mask:0xf bank_mask:0xc
	v_mov_b32_dpp v93, v167 row_shr:8 row_mask:0xf bank_mask:0xc
	v_mov_b32_dpp v94, v168 row_shr:8 row_mask:0xf bank_mask:0xc
	v_mov_b32_dpp v95, v169 row_shr:8 row_mask:0xf bank_mask:0xc
	v_mov_b32_e32 v166, v104
	v_mov_b32_e32 v167, v105
	v_mov_b32_e32 v168, v106
	v_mov_b32_e32 v169, v107
	v_mov_b32_dpp v104, v100 row_shl:8 row_mask:0xf bank_mask:0x3
	v_mov_b32_dpp v105, v101 row_shl:8 row_mask:0xf bank_mask:0x3
	v_mov_b32_dpp v106, v102 row_shl:8 row_mask:0xf bank_mask:0x3
	v_mov_b32_dpp v107, v103 row_shl:8 row_mask:0xf bank_mask:0x3
	v_mov_b32_dpp v100, v166 row_shr:8 row_mask:0xf bank_mask:0xc
	v_mov_b32_dpp v101, v167 row_shr:8 row_mask:0xf bank_mask:0xc
	v_mov_b32_dpp v102, v168 row_shr:8 row_mask:0xf bank_mask:0xc
	v_mov_b32_dpp v103, v169 row_shr:8 row_mask:0xf bank_mask:0xc
	v_mov_b32_e32 v166, v112
	v_mov_b32_e32 v167, v113
	v_mov_b32_e32 v168, v114
	v_mov_b32_e32 v169, v115
	v_mov_b32_dpp v112, v108 row_shl:8 row_mask:0xf bank_mask:0x3
	v_mov_b32_dpp v113, v109 row_shl:8 row_mask:0xf bank_mask:0x3
	v_mov_b32_dpp v114, v110 row_shl:8 row_mask:0xf bank_mask:0x3
	v_mov_b32_dpp v115, v111 row_shl:8 row_mask:0xf bank_mask:0x3
	v_mov_b32_dpp v108, v166 row_shr:8 row_mask:0xf bank_mask:0xc
	v_mov_b32_dpp v109, v167 row_shr:8 row_mask:0xf bank_mask:0xc
	v_mov_b32_dpp v110, v168 row_shr:8 row_mask:0xf bank_mask:0xc
	v_mov_b32_dpp v111, v169 row_shr:8 row_mask:0xf bank_mask:0xc
	v_mov_b32_e32 v166, v120
	v_mov_b32_e32 v167, v121
	v_mov_b32_e32 v168, v122
	v_mov_b32_e32 v169, v123
	v_mov_b32_dpp v120, v116 row_shl:8 row_mask:0xf bank_mask:0x3
	v_mov_b32_dpp v121, v117 row_shl:8 row_mask:0xf bank_mask:0x3
	v_mov_b32_dpp v122, v118 row_shl:8 row_mask:0xf bank_mask:0x3
	v_mov_b32_dpp v123, v119 row_shl:8 row_mask:0xf bank_mask:0x3
	v_mov_b32_dpp v116, v166 row_shr:8 row_mask:0xf bank_mask:0xc
	v_mov_b32_dpp v117, v167 row_shr:8 row_mask:0xf bank_mask:0xc
	v_mov_b32_dpp v118, v168 row_shr:8 row_mask:0xf bank_mask:0xc
	v_mov_b32_dpp v119, v169 row_shr:8 row_mask:0xf bank_mask:0xc
	v_mfma_f32_16x16x32_bf16 v[198:201], v[84:87], v[92:95], v[198:201]
	v_mfma_f32_16x16x32_bf16 v[202:205], v[84:87], v[100:103], v[202:205]
	v_mfma_f32_16x16x32_bf16 v[206:209], v[84:87], v[108:111], v[206:209]
	v_mfma_f32_16x16x32_bf16 v[210:213], v[84:87], v[116:119], v[210:213]
	v_mfma_f32_16x16x32_bf16 v[198:201], v[88:91], v[96:99], v[198:201]
	v_mfma_f32_16x16x32_bf16 v[202:205], v[88:91], v[104:107], v[202:205]
	v_mfma_f32_16x16x32_bf16 v[206:209], v[88:91], v[112:115], v[206:209]
	v_mfma_f32_16x16x32_bf16 v[210:213], v[88:91], v[120:123], v[210:213]
	global_load_dwordx4 v[84:87], v[170:171], off offset:768
	global_load_dwordx4 v[88:91], v[172:173], off offset:768
	global_load_dwordx4 v[92:95], v[174:175], off offset:768
	global_load_dwordx4 v[96:99], v[176:177], off offset:768
	global_load_dwordx4 v[100:103], v[178:179], off offset:768
	global_load_dwordx4 v[104:107], v[180:181], off offset:768
	global_load_dwordx4 v[108:111], v[184:185], off offset:768
	global_load_dwordx4 v[112:115], v[186:187], off offset:768
	global_load_dwordx4 v[116:119], v[190:191], off offset:768
	global_load_dwordx4 v[120:123], v[192:193], off offset:768
	s_waitcnt vmcnt(10)
	v_mov_b32_e32 v166, v128
	v_mov_b32_e32 v167, v129
	v_mov_b32_e32 v168, v130
	v_mov_b32_e32 v169, v131
	v_mov_b32_dpp v128, v124 row_shl:8 row_mask:0xf bank_mask:0x3
	v_mov_b32_dpp v129, v125 row_shl:8 row_mask:0xf bank_mask:0x3
	v_mov_b32_dpp v130, v126 row_shl:8 row_mask:0xf bank_mask:0x3
	v_mov_b32_dpp v131, v127 row_shl:8 row_mask:0xf bank_mask:0x3
	v_mov_b32_dpp v124, v166 row_shr:8 row_mask:0xf bank_mask:0xc
	v_mov_b32_dpp v125, v167 row_shr:8 row_mask:0xf bank_mask:0xc
	v_mov_b32_dpp v126, v168 row_shr:8 row_mask:0xf bank_mask:0xc
	v_mov_b32_dpp v127, v169 row_shr:8 row_mask:0xf bank_mask:0xc
	v_mov_b32_e32 v166, v136
	v_mov_b32_e32 v167, v137
	v_mov_b32_e32 v168, v138
	v_mov_b32_e32 v169, v139
	v_mov_b32_dpp v136, v132 row_shl:8 row_mask:0xf bank_mask:0x3
	v_mov_b32_dpp v137, v133 row_shl:8 row_mask:0xf bank_mask:0x3
	v_mov_b32_dpp v138, v134 row_shl:8 row_mask:0xf bank_mask:0x3
	v_mov_b32_dpp v139, v135 row_shl:8 row_mask:0xf bank_mask:0x3
	v_mov_b32_dpp v132, v166 row_shr:8 row_mask:0xf bank_mask:0xc
	v_mov_b32_dpp v133, v167 row_shr:8 row_mask:0xf bank_mask:0xc
	v_mov_b32_dpp v134, v168 row_shr:8 row_mask:0xf bank_mask:0xc
	v_mov_b32_dpp v135, v169 row_shr:8 row_mask:0xf bank_mask:0xc
	v_mov_b32_e32 v166, v146
	v_mov_b32_e32 v167, v147
	v_mov_b32_e32 v168, v148
	v_mov_b32_e32 v169, v149
	v_mov_b32_dpp v146, v140 row_shl:8 row_mask:0xf bank_mask:0x3
	v_mov_b32_dpp v147, v141 row_shl:8 row_mask:0xf bank_mask:0x3
	v_mov_b32_dpp v148, v142 row_shl:8 row_mask:0xf bank_mask:0x3
	v_mov_b32_dpp v149, v143 row_shl:8 row_mask:0xf bank_mask:0x3
	v_mov_b32_dpp v140, v166 row_shr:8 row_mask:0xf bank_mask:0xc
	v_mov_b32_dpp v141, v167 row_shr:8 row_mask:0xf bank_mask:0xc
	v_mov_b32_dpp v142, v168 row_shr:8 row_mask:0xf bank_mask:0xc
	v_mov_b32_dpp v143, v169 row_shr:8 row_mask:0xf bank_mask:0xc
	v_mov_b32_e32 v166, v154
	v_mov_b32_e32 v167, v155
	v_mov_b32_e32 v168, v156
	v_mov_b32_e32 v169, v157
	v_mov_b32_dpp v154, v150 row_shl:8 row_mask:0xf bank_mask:0x3
	v_mov_b32_dpp v155, v151 row_shl:8 row_mask:0xf bank_mask:0x3
	v_mov_b32_dpp v156, v152 row_shl:8 row_mask:0xf bank_mask:0x3
	v_mov_b32_dpp v157, v153 row_shl:8 row_mask:0xf bank_mask:0x3
	v_mov_b32_dpp v150, v166 row_shr:8 row_mask:0xf bank_mask:0xc
	v_mov_b32_dpp v151, v167 row_shr:8 row_mask:0xf bank_mask:0xc
	v_mov_b32_dpp v152, v168 row_shr:8 row_mask:0xf bank_mask:0xc
	v_mov_b32_dpp v153, v169 row_shr:8 row_mask:0xf bank_mask:0xc
	v_mov_b32_e32 v166, v162
	v_mov_b32_e32 v167, v163
	v_mov_b32_e32 v168, v164
	v_mov_b32_e32 v169, v165
	v_mov_b32_dpp v162, v158 row_shl:8 row_mask:0xf bank_mask:0x3
	v_mov_b32_dpp v163, v159 row_shl:8 row_mask:0xf bank_mask:0x3
	v_mov_b32_dpp v164, v160 row_shl:8 row_mask:0xf bank_mask:0x3
	v_mov_b32_dpp v165, v161 row_shl:8 row_mask:0xf bank_mask:0x3
	v_mov_b32_dpp v158, v166 row_shr:8 row_mask:0xf bank_mask:0xc
	v_mov_b32_dpp v159, v167 row_shr:8 row_mask:0xf bank_mask:0xc
	v_mov_b32_dpp v160, v168 row_shr:8 row_mask:0xf bank_mask:0xc
	v_mov_b32_dpp v161, v169 row_shr:8 row_mask:0xf bank_mask:0xc
	v_mfma_f32_16x16x32_bf16 v[198:201], v[124:127], v[132:135], v[198:201]
	v_mfma_f32_16x16x32_bf16 v[202:205], v[124:127], v[140:143], v[202:205]
	v_mfma_f32_16x16x32_bf16 v[206:209], v[124:127], v[150:153], v[206:209]
	v_mfma_f32_16x16x32_bf16 v[210:213], v[124:127], v[158:161], v[210:213]
	v_mfma_f32_16x16x32_bf16 v[198:201], v[128:131], v[136:139], v[198:201]
	v_mfma_f32_16x16x32_bf16 v[202:205], v[128:131], v[146:149], v[202:205]
	v_mfma_f32_16x16x32_bf16 v[206:209], v[128:131], v[154:157], v[206:209]
	v_mfma_f32_16x16x32_bf16 v[210:213], v[128:131], v[162:165], v[210:213]
	global_load_dwordx4 v[124:127], v[170:171], off offset:896
	global_load_dwordx4 v[128:131], v[172:173], off offset:896
	global_load_dwordx4 v[132:135], v[174:175], off offset:896
	global_load_dwordx4 v[136:139], v[176:177], off offset:896
	global_load_dwordx4 v[140:143], v[178:179], off offset:896
	global_load_dwordx4 v[146:149], v[180:181], off offset:896
	global_load_dwordx4 v[150:153], v[184:185], off offset:896
	global_load_dwordx4 v[154:157], v[186:187], off offset:896
	global_load_dwordx4 v[158:161], v[190:191], off offset:896
	global_load_dwordx4 v[162:165], v[192:193], off offset:896
	s_waitcnt vmcnt(10)
	v_mov_b32_e32 v166, v88
	v_mov_b32_e32 v167, v89
	v_mov_b32_e32 v168, v90
	v_mov_b32_e32 v169, v91
	v_mov_b32_dpp v88, v84 row_shl:8 row_mask:0xf bank_mask:0x3
	v_mov_b32_dpp v89, v85 row_shl:8 row_mask:0xf bank_mask:0x3
	v_mov_b32_dpp v90, v86 row_shl:8 row_mask:0xf bank_mask:0x3
	v_mov_b32_dpp v91, v87 row_shl:8 row_mask:0xf bank_mask:0x3
	v_mov_b32_dpp v84, v166 row_shr:8 row_mask:0xf bank_mask:0xc
	v_mov_b32_dpp v85, v167 row_shr:8 row_mask:0xf bank_mask:0xc
	v_mov_b32_dpp v86, v168 row_shr:8 row_mask:0xf bank_mask:0xc
	v_mov_b32_dpp v87, v169 row_shr:8 row_mask:0xf bank_mask:0xc
	v_mov_b32_e32 v166, v96
	v_mov_b32_e32 v167, v97
	v_mov_b32_e32 v168, v98
	v_mov_b32_e32 v169, v99
	v_mov_b32_dpp v96, v92 row_shl:8 row_mask:0xf bank_mask:0x3
	v_mov_b32_dpp v97, v93 row_shl:8 row_mask:0xf bank_mask:0x3
	v_mov_b32_dpp v98, v94 row_shl:8 row_mask:0xf bank_mask:0x3
	v_mov_b32_dpp v99, v95 row_shl:8 row_mask:0xf bank_mask:0x3
	v_mov_b32_dpp v92, v166 row_shr:8 row_mask:0xf bank_mask:0xc
	v_mov_b32_dpp v93, v167 row_shr:8 row_mask:0xf bank_mask:0xc
	v_mov_b32_dpp v94, v168 row_shr:8 row_mask:0xf bank_mask:0xc
	v_mov_b32_dpp v95, v169 row_shr:8 row_mask:0xf bank_mask:0xc
	v_mov_b32_e32 v166, v104
	v_mov_b32_e32 v167, v105
	v_mov_b32_e32 v168, v106
	v_mov_b32_e32 v169, v107
	v_mov_b32_dpp v104, v100 row_shl:8 row_mask:0xf bank_mask:0x3
	v_mov_b32_dpp v105, v101 row_shl:8 row_mask:0xf bank_mask:0x3
	v_mov_b32_dpp v106, v102 row_shl:8 row_mask:0xf bank_mask:0x3
	v_mov_b32_dpp v107, v103 row_shl:8 row_mask:0xf bank_mask:0x3
	v_mov_b32_dpp v100, v166 row_shr:8 row_mask:0xf bank_mask:0xc
	v_mov_b32_dpp v101, v167 row_shr:8 row_mask:0xf bank_mask:0xc
	v_mov_b32_dpp v102, v168 row_shr:8 row_mask:0xf bank_mask:0xc
	v_mov_b32_dpp v103, v169 row_shr:8 row_mask:0xf bank_mask:0xc
	v_mov_b32_e32 v166, v112
	v_mov_b32_e32 v167, v113
	v_mov_b32_e32 v168, v114
	v_mov_b32_e32 v169, v115
	v_mov_b32_dpp v112, v108 row_shl:8 row_mask:0xf bank_mask:0x3
	v_mov_b32_dpp v113, v109 row_shl:8 row_mask:0xf bank_mask:0x3
	v_mov_b32_dpp v114, v110 row_shl:8 row_mask:0xf bank_mask:0x3
	v_mov_b32_dpp v115, v111 row_shl:8 row_mask:0xf bank_mask:0x3
	v_mov_b32_dpp v108, v166 row_shr:8 row_mask:0xf bank_mask:0xc
	v_mov_b32_dpp v109, v167 row_shr:8 row_mask:0xf bank_mask:0xc
	v_mov_b32_dpp v110, v168 row_shr:8 row_mask:0xf bank_mask:0xc
	v_mov_b32_dpp v111, v169 row_shr:8 row_mask:0xf bank_mask:0xc
	v_mov_b32_e32 v166, v120
	v_mov_b32_e32 v167, v121
	v_mov_b32_e32 v168, v122
	v_mov_b32_e32 v169, v123
	v_mov_b32_dpp v120, v116 row_shl:8 row_mask:0xf bank_mask:0x3
	v_mov_b32_dpp v121, v117 row_shl:8 row_mask:0xf bank_mask:0x3
	v_mov_b32_dpp v122, v118 row_shl:8 row_mask:0xf bank_mask:0x3
	v_mov_b32_dpp v123, v119 row_shl:8 row_mask:0xf bank_mask:0x3
	v_mov_b32_dpp v116, v166 row_shr:8 row_mask:0xf bank_mask:0xc
	v_mov_b32_dpp v117, v167 row_shr:8 row_mask:0xf bank_mask:0xc
	v_mov_b32_dpp v118, v168 row_shr:8 row_mask:0xf bank_mask:0xc
	v_mov_b32_dpp v119, v169 row_shr:8 row_mask:0xf bank_mask:0xc
	v_mfma_f32_16x16x32_bf16 v[198:201], v[84:87], v[92:95], v[198:201]
	v_mfma_f32_16x16x32_bf16 v[202:205], v[84:87], v[100:103], v[202:205]
	v_mfma_f32_16x16x32_bf16 v[206:209], v[84:87], v[108:111], v[206:209]
	v_mfma_f32_16x16x32_bf16 v[210:213], v[84:87], v[116:119], v[210:213]
	v_mfma_f32_16x16x32_bf16 v[198:201], v[88:91], v[96:99], v[198:201]
	v_mfma_f32_16x16x32_bf16 v[202:205], v[88:91], v[104:107], v[202:205]
	v_mfma_f32_16x16x32_bf16 v[206:209], v[88:91], v[112:115], v[206:209]
	v_mfma_f32_16x16x32_bf16 v[210:213], v[88:91], v[120:123], v[210:213]
	global_load_dwordx4 v[84:87], v[170:171], off offset:1024
	global_load_dwordx4 v[88:91], v[172:173], off offset:1024
	global_load_dwordx4 v[92:95], v[174:175], off offset:1024
	global_load_dwordx4 v[96:99], v[176:177], off offset:1024
	global_load_dwordx4 v[100:103], v[178:179], off offset:1024
	global_load_dwordx4 v[104:107], v[180:181], off offset:1024
	global_load_dwordx4 v[108:111], v[184:185], off offset:1024
	global_load_dwordx4 v[112:115], v[186:187], off offset:1024
	global_load_dwordx4 v[116:119], v[190:191], off offset:1024
	global_load_dwordx4 v[120:123], v[192:193], off offset:1024
	s_waitcnt vmcnt(10)
	v_mov_b32_e32 v166, v128
	v_mov_b32_e32 v167, v129
	v_mov_b32_e32 v168, v130
	v_mov_b32_e32 v169, v131
	v_mov_b32_dpp v128, v124 row_shl:8 row_mask:0xf bank_mask:0x3
	v_mov_b32_dpp v129, v125 row_shl:8 row_mask:0xf bank_mask:0x3
	v_mov_b32_dpp v130, v126 row_shl:8 row_mask:0xf bank_mask:0x3
	v_mov_b32_dpp v131, v127 row_shl:8 row_mask:0xf bank_mask:0x3
	v_mov_b32_dpp v124, v166 row_shr:8 row_mask:0xf bank_mask:0xc
	v_mov_b32_dpp v125, v167 row_shr:8 row_mask:0xf bank_mask:0xc
	v_mov_b32_dpp v126, v168 row_shr:8 row_mask:0xf bank_mask:0xc
	v_mov_b32_dpp v127, v169 row_shr:8 row_mask:0xf bank_mask:0xc
	v_mov_b32_e32 v166, v136
	v_mov_b32_e32 v167, v137
	v_mov_b32_e32 v168, v138
	v_mov_b32_e32 v169, v139
	v_mov_b32_dpp v136, v132 row_shl:8 row_mask:0xf bank_mask:0x3
	v_mov_b32_dpp v137, v133 row_shl:8 row_mask:0xf bank_mask:0x3
	v_mov_b32_dpp v138, v134 row_shl:8 row_mask:0xf bank_mask:0x3
	v_mov_b32_dpp v139, v135 row_shl:8 row_mask:0xf bank_mask:0x3
	v_mov_b32_dpp v132, v166 row_shr:8 row_mask:0xf bank_mask:0xc
	v_mov_b32_dpp v133, v167 row_shr:8 row_mask:0xf bank_mask:0xc
	v_mov_b32_dpp v134, v168 row_shr:8 row_mask:0xf bank_mask:0xc
	v_mov_b32_dpp v135, v169 row_shr:8 row_mask:0xf bank_mask:0xc
	v_mov_b32_e32 v166, v146
	v_mov_b32_e32 v167, v147
	v_mov_b32_e32 v168, v148
	v_mov_b32_e32 v169, v149
	v_mov_b32_dpp v146, v140 row_shl:8 row_mask:0xf bank_mask:0x3
	v_mov_b32_dpp v147, v141 row_shl:8 row_mask:0xf bank_mask:0x3
	v_mov_b32_dpp v148, v142 row_shl:8 row_mask:0xf bank_mask:0x3
	v_mov_b32_dpp v149, v143 row_shl:8 row_mask:0xf bank_mask:0x3
	v_mov_b32_dpp v140, v166 row_shr:8 row_mask:0xf bank_mask:0xc
	v_mov_b32_dpp v141, v167 row_shr:8 row_mask:0xf bank_mask:0xc
	v_mov_b32_dpp v142, v168 row_shr:8 row_mask:0xf bank_mask:0xc
	v_mov_b32_dpp v143, v169 row_shr:8 row_mask:0xf bank_mask:0xc
	v_mov_b32_e32 v166, v154
	v_mov_b32_e32 v167, v155
	v_mov_b32_e32 v168, v156
	v_mov_b32_e32 v169, v157
	v_mov_b32_dpp v154, v150 row_shl:8 row_mask:0xf bank_mask:0x3
	v_mov_b32_dpp v155, v151 row_shl:8 row_mask:0xf bank_mask:0x3
	v_mov_b32_dpp v156, v152 row_shl:8 row_mask:0xf bank_mask:0x3
	v_mov_b32_dpp v157, v153 row_shl:8 row_mask:0xf bank_mask:0x3
	v_mov_b32_dpp v150, v166 row_shr:8 row_mask:0xf bank_mask:0xc
	v_mov_b32_dpp v151, v167 row_shr:8 row_mask:0xf bank_mask:0xc
	v_mov_b32_dpp v152, v168 row_shr:8 row_mask:0xf bank_mask:0xc
	v_mov_b32_dpp v153, v169 row_shr:8 row_mask:0xf bank_mask:0xc
	v_mov_b32_e32 v166, v162
	v_mov_b32_e32 v167, v163
	v_mov_b32_e32 v168, v164
	v_mov_b32_e32 v169, v165
	v_mov_b32_dpp v162, v158 row_shl:8 row_mask:0xf bank_mask:0x3
	v_mov_b32_dpp v163, v159 row_shl:8 row_mask:0xf bank_mask:0x3
	v_mov_b32_dpp v164, v160 row_shl:8 row_mask:0xf bank_mask:0x3
	v_mov_b32_dpp v165, v161 row_shl:8 row_mask:0xf bank_mask:0x3
	v_mov_b32_dpp v158, v166 row_shr:8 row_mask:0xf bank_mask:0xc
	v_mov_b32_dpp v159, v167 row_shr:8 row_mask:0xf bank_mask:0xc
	v_mov_b32_dpp v160, v168 row_shr:8 row_mask:0xf bank_mask:0xc
	v_mov_b32_dpp v161, v169 row_shr:8 row_mask:0xf bank_mask:0xc
	v_mfma_f32_16x16x32_bf16 v[198:201], v[124:127], v[132:135], v[198:201]
	v_mfma_f32_16x16x32_bf16 v[202:205], v[124:127], v[140:143], v[202:205]
	v_mfma_f32_16x16x32_bf16 v[206:209], v[124:127], v[150:153], v[206:209]
	v_mfma_f32_16x16x32_bf16 v[210:213], v[124:127], v[158:161], v[210:213]
	v_mfma_f32_16x16x32_bf16 v[198:201], v[128:131], v[136:139], v[198:201]
	v_mfma_f32_16x16x32_bf16 v[202:205], v[128:131], v[146:149], v[202:205]
	v_mfma_f32_16x16x32_bf16 v[206:209], v[128:131], v[154:157], v[206:209]
	v_mfma_f32_16x16x32_bf16 v[210:213], v[128:131], v[162:165], v[210:213]
	global_load_dwordx4 v[124:127], v[170:171], off offset:1152
	global_load_dwordx4 v[128:131], v[172:173], off offset:1152
	global_load_dwordx4 v[132:135], v[174:175], off offset:1152
	global_load_dwordx4 v[136:139], v[176:177], off offset:1152
	global_load_dwordx4 v[140:143], v[178:179], off offset:1152
	global_load_dwordx4 v[146:149], v[180:181], off offset:1152
	global_load_dwordx4 v[150:153], v[184:185], off offset:1152
	global_load_dwordx4 v[154:157], v[186:187], off offset:1152
	global_load_dwordx4 v[158:161], v[190:191], off offset:1152
	global_load_dwordx4 v[162:165], v[192:193], off offset:1152
	s_waitcnt vmcnt(10)
	v_mov_b32_e32 v166, v88
	v_mov_b32_e32 v167, v89
	v_mov_b32_e32 v168, v90
	v_mov_b32_e32 v169, v91
	v_mov_b32_dpp v88, v84 row_shl:8 row_mask:0xf bank_mask:0x3
	v_mov_b32_dpp v89, v85 row_shl:8 row_mask:0xf bank_mask:0x3
	v_mov_b32_dpp v90, v86 row_shl:8 row_mask:0xf bank_mask:0x3
	v_mov_b32_dpp v91, v87 row_shl:8 row_mask:0xf bank_mask:0x3
	v_mov_b32_dpp v84, v166 row_shr:8 row_mask:0xf bank_mask:0xc
	v_mov_b32_dpp v85, v167 row_shr:8 row_mask:0xf bank_mask:0xc
	v_mov_b32_dpp v86, v168 row_shr:8 row_mask:0xf bank_mask:0xc
	v_mov_b32_dpp v87, v169 row_shr:8 row_mask:0xf bank_mask:0xc
	v_mov_b32_e32 v166, v96
	v_mov_b32_e32 v167, v97
	v_mov_b32_e32 v168, v98
	v_mov_b32_e32 v169, v99
	v_mov_b32_dpp v96, v92 row_shl:8 row_mask:0xf bank_mask:0x3
	v_mov_b32_dpp v97, v93 row_shl:8 row_mask:0xf bank_mask:0x3
	v_mov_b32_dpp v98, v94 row_shl:8 row_mask:0xf bank_mask:0x3
	v_mov_b32_dpp v99, v95 row_shl:8 row_mask:0xf bank_mask:0x3
	v_mov_b32_dpp v92, v166 row_shr:8 row_mask:0xf bank_mask:0xc
	v_mov_b32_dpp v93, v167 row_shr:8 row_mask:0xf bank_mask:0xc
	v_mov_b32_dpp v94, v168 row_shr:8 row_mask:0xf bank_mask:0xc
	v_mov_b32_dpp v95, v169 row_shr:8 row_mask:0xf bank_mask:0xc
	v_mov_b32_e32 v166, v104
	v_mov_b32_e32 v167, v105
	v_mov_b32_e32 v168, v106
	v_mov_b32_e32 v169, v107
	v_mov_b32_dpp v104, v100 row_shl:8 row_mask:0xf bank_mask:0x3
	v_mov_b32_dpp v105, v101 row_shl:8 row_mask:0xf bank_mask:0x3
	v_mov_b32_dpp v106, v102 row_shl:8 row_mask:0xf bank_mask:0x3
	v_mov_b32_dpp v107, v103 row_shl:8 row_mask:0xf bank_mask:0x3
	v_mov_b32_dpp v100, v166 row_shr:8 row_mask:0xf bank_mask:0xc
	v_mov_b32_dpp v101, v167 row_shr:8 row_mask:0xf bank_mask:0xc
	v_mov_b32_dpp v102, v168 row_shr:8 row_mask:0xf bank_mask:0xc
	v_mov_b32_dpp v103, v169 row_shr:8 row_mask:0xf bank_mask:0xc
	v_mov_b32_e32 v166, v112
	v_mov_b32_e32 v167, v113
	v_mov_b32_e32 v168, v114
	v_mov_b32_e32 v169, v115
	v_mov_b32_dpp v112, v108 row_shl:8 row_mask:0xf bank_mask:0x3
	v_mov_b32_dpp v113, v109 row_shl:8 row_mask:0xf bank_mask:0x3
	v_mov_b32_dpp v114, v110 row_shl:8 row_mask:0xf bank_mask:0x3
	v_mov_b32_dpp v115, v111 row_shl:8 row_mask:0xf bank_mask:0x3
	v_mov_b32_dpp v108, v166 row_shr:8 row_mask:0xf bank_mask:0xc
	v_mov_b32_dpp v109, v167 row_shr:8 row_mask:0xf bank_mask:0xc
	v_mov_b32_dpp v110, v168 row_shr:8 row_mask:0xf bank_mask:0xc
	v_mov_b32_dpp v111, v169 row_shr:8 row_mask:0xf bank_mask:0xc
	v_mov_b32_e32 v166, v120
	v_mov_b32_e32 v167, v121
	v_mov_b32_e32 v168, v122
	v_mov_b32_e32 v169, v123
	v_mov_b32_dpp v120, v116 row_shl:8 row_mask:0xf bank_mask:0x3
	v_mov_b32_dpp v121, v117 row_shl:8 row_mask:0xf bank_mask:0x3
	v_mov_b32_dpp v122, v118 row_shl:8 row_mask:0xf bank_mask:0x3
	v_mov_b32_dpp v123, v119 row_shl:8 row_mask:0xf bank_mask:0x3
	v_mov_b32_dpp v116, v166 row_shr:8 row_mask:0xf bank_mask:0xc
	v_mov_b32_dpp v117, v167 row_shr:8 row_mask:0xf bank_mask:0xc
	v_mov_b32_dpp v118, v168 row_shr:8 row_mask:0xf bank_mask:0xc
	v_mov_b32_dpp v119, v169 row_shr:8 row_mask:0xf bank_mask:0xc
	v_mfma_f32_16x16x32_bf16 v[198:201], v[84:87], v[92:95], v[198:201]
	v_mfma_f32_16x16x32_bf16 v[202:205], v[84:87], v[100:103], v[202:205]
	v_mfma_f32_16x16x32_bf16 v[206:209], v[84:87], v[108:111], v[206:209]
	v_mfma_f32_16x16x32_bf16 v[210:213], v[84:87], v[116:119], v[210:213]
	v_mfma_f32_16x16x32_bf16 v[198:201], v[88:91], v[96:99], v[198:201]
	v_mfma_f32_16x16x32_bf16 v[202:205], v[88:91], v[104:107], v[202:205]
	v_mfma_f32_16x16x32_bf16 v[206:209], v[88:91], v[112:115], v[206:209]
	v_mfma_f32_16x16x32_bf16 v[210:213], v[88:91], v[120:123], v[210:213]
	global_load_dwordx4 v[84:87], v[170:171], off offset:1280
	global_load_dwordx4 v[88:91], v[172:173], off offset:1280
	global_load_dwordx4 v[92:95], v[174:175], off offset:1280
	global_load_dwordx4 v[96:99], v[176:177], off offset:1280
	global_load_dwordx4 v[100:103], v[178:179], off offset:1280
	global_load_dwordx4 v[104:107], v[180:181], off offset:1280
	global_load_dwordx4 v[108:111], v[184:185], off offset:1280
	global_load_dwordx4 v[112:115], v[186:187], off offset:1280
	global_load_dwordx4 v[116:119], v[190:191], off offset:1280
	global_load_dwordx4 v[120:123], v[192:193], off offset:1280
	s_waitcnt vmcnt(10)
	v_mov_b32_e32 v166, v128
	v_mov_b32_e32 v167, v129
	v_mov_b32_e32 v168, v130
	v_mov_b32_e32 v169, v131
	v_mov_b32_dpp v128, v124 row_shl:8 row_mask:0xf bank_mask:0x3
	v_mov_b32_dpp v129, v125 row_shl:8 row_mask:0xf bank_mask:0x3
	v_mov_b32_dpp v130, v126 row_shl:8 row_mask:0xf bank_mask:0x3
	v_mov_b32_dpp v131, v127 row_shl:8 row_mask:0xf bank_mask:0x3
	v_mov_b32_dpp v124, v166 row_shr:8 row_mask:0xf bank_mask:0xc
	v_mov_b32_dpp v125, v167 row_shr:8 row_mask:0xf bank_mask:0xc
	v_mov_b32_dpp v126, v168 row_shr:8 row_mask:0xf bank_mask:0xc
	v_mov_b32_dpp v127, v169 row_shr:8 row_mask:0xf bank_mask:0xc
	v_mov_b32_e32 v166, v136
	v_mov_b32_e32 v167, v137
	v_mov_b32_e32 v168, v138
	v_mov_b32_e32 v169, v139
	v_mov_b32_dpp v136, v132 row_shl:8 row_mask:0xf bank_mask:0x3
	v_mov_b32_dpp v137, v133 row_shl:8 row_mask:0xf bank_mask:0x3
	v_mov_b32_dpp v138, v134 row_shl:8 row_mask:0xf bank_mask:0x3
	v_mov_b32_dpp v139, v135 row_shl:8 row_mask:0xf bank_mask:0x3
	v_mov_b32_dpp v132, v166 row_shr:8 row_mask:0xf bank_mask:0xc
	v_mov_b32_dpp v133, v167 row_shr:8 row_mask:0xf bank_mask:0xc
	v_mov_b32_dpp v134, v168 row_shr:8 row_mask:0xf bank_mask:0xc
	v_mov_b32_dpp v135, v169 row_shr:8 row_mask:0xf bank_mask:0xc
	v_mov_b32_e32 v166, v146
	v_mov_b32_e32 v167, v147
	v_mov_b32_e32 v168, v148
	v_mov_b32_e32 v169, v149
	v_mov_b32_dpp v146, v140 row_shl:8 row_mask:0xf bank_mask:0x3
	v_mov_b32_dpp v147, v141 row_shl:8 row_mask:0xf bank_mask:0x3
	v_mov_b32_dpp v148, v142 row_shl:8 row_mask:0xf bank_mask:0x3
	v_mov_b32_dpp v149, v143 row_shl:8 row_mask:0xf bank_mask:0x3
	v_mov_b32_dpp v140, v166 row_shr:8 row_mask:0xf bank_mask:0xc
	v_mov_b32_dpp v141, v167 row_shr:8 row_mask:0xf bank_mask:0xc
	v_mov_b32_dpp v142, v168 row_shr:8 row_mask:0xf bank_mask:0xc
	v_mov_b32_dpp v143, v169 row_shr:8 row_mask:0xf bank_mask:0xc
	v_mov_b32_e32 v166, v154
	v_mov_b32_e32 v167, v155
	v_mov_b32_e32 v168, v156
	v_mov_b32_e32 v169, v157
	v_mov_b32_dpp v154, v150 row_shl:8 row_mask:0xf bank_mask:0x3
	v_mov_b32_dpp v155, v151 row_shl:8 row_mask:0xf bank_mask:0x3
	v_mov_b32_dpp v156, v152 row_shl:8 row_mask:0xf bank_mask:0x3
	v_mov_b32_dpp v157, v153 row_shl:8 row_mask:0xf bank_mask:0x3
	v_mov_b32_dpp v150, v166 row_shr:8 row_mask:0xf bank_mask:0xc
	v_mov_b32_dpp v151, v167 row_shr:8 row_mask:0xf bank_mask:0xc
	v_mov_b32_dpp v152, v168 row_shr:8 row_mask:0xf bank_mask:0xc
	v_mov_b32_dpp v153, v169 row_shr:8 row_mask:0xf bank_mask:0xc
	v_mov_b32_e32 v166, v162
	v_mov_b32_e32 v167, v163
	v_mov_b32_e32 v168, v164
	v_mov_b32_e32 v169, v165
	v_mov_b32_dpp v162, v158 row_shl:8 row_mask:0xf bank_mask:0x3
	v_mov_b32_dpp v163, v159 row_shl:8 row_mask:0xf bank_mask:0x3
	v_mov_b32_dpp v164, v160 row_shl:8 row_mask:0xf bank_mask:0x3
	v_mov_b32_dpp v165, v161 row_shl:8 row_mask:0xf bank_mask:0x3
	v_mov_b32_dpp v158, v166 row_shr:8 row_mask:0xf bank_mask:0xc
	v_mov_b32_dpp v159, v167 row_shr:8 row_mask:0xf bank_mask:0xc
	v_mov_b32_dpp v160, v168 row_shr:8 row_mask:0xf bank_mask:0xc
	v_mov_b32_dpp v161, v169 row_shr:8 row_mask:0xf bank_mask:0xc
	v_mfma_f32_16x16x32_bf16 v[198:201], v[124:127], v[132:135], v[198:201]
	v_mfma_f32_16x16x32_bf16 v[202:205], v[124:127], v[140:143], v[202:205]
	v_mfma_f32_16x16x32_bf16 v[206:209], v[124:127], v[150:153], v[206:209]
	v_mfma_f32_16x16x32_bf16 v[210:213], v[124:127], v[158:161], v[210:213]
	v_mfma_f32_16x16x32_bf16 v[198:201], v[128:131], v[136:139], v[198:201]
	v_mfma_f32_16x16x32_bf16 v[202:205], v[128:131], v[146:149], v[202:205]
	v_mfma_f32_16x16x32_bf16 v[206:209], v[128:131], v[154:157], v[206:209]
	v_mfma_f32_16x16x32_bf16 v[210:213], v[128:131], v[162:165], v[210:213]
	s_waitcnt vmcnt(0)
	v_mov_b32_e32 v166, v88
	v_mov_b32_e32 v167, v89
	v_mov_b32_e32 v168, v90
	v_mov_b32_e32 v169, v91
	v_mov_b32_dpp v88, v84 row_shl:8 row_mask:0xf bank_mask:0x3
	v_mov_b32_dpp v89, v85 row_shl:8 row_mask:0xf bank_mask:0x3
	v_mov_b32_dpp v90, v86 row_shl:8 row_mask:0xf bank_mask:0x3
	v_mov_b32_dpp v91, v87 row_shl:8 row_mask:0xf bank_mask:0x3
	v_mov_b32_dpp v84, v166 row_shr:8 row_mask:0xf bank_mask:0xc
	v_mov_b32_dpp v85, v167 row_shr:8 row_mask:0xf bank_mask:0xc
	v_mov_b32_dpp v86, v168 row_shr:8 row_mask:0xf bank_mask:0xc
	v_mov_b32_dpp v87, v169 row_shr:8 row_mask:0xf bank_mask:0xc
	v_mov_b32_e32 v166, v96
	v_mov_b32_e32 v167, v97
	v_mov_b32_e32 v168, v98
	v_mov_b32_e32 v169, v99
	v_mov_b32_dpp v96, v92 row_shl:8 row_mask:0xf bank_mask:0x3
	v_mov_b32_dpp v97, v93 row_shl:8 row_mask:0xf bank_mask:0x3
	v_mov_b32_dpp v98, v94 row_shl:8 row_mask:0xf bank_mask:0x3
	v_mov_b32_dpp v99, v95 row_shl:8 row_mask:0xf bank_mask:0x3
	v_mov_b32_dpp v92, v166 row_shr:8 row_mask:0xf bank_mask:0xc
	v_mov_b32_dpp v93, v167 row_shr:8 row_mask:0xf bank_mask:0xc
	v_mov_b32_dpp v94, v168 row_shr:8 row_mask:0xf bank_mask:0xc
	v_mov_b32_dpp v95, v169 row_shr:8 row_mask:0xf bank_mask:0xc
	v_mov_b32_e32 v166, v104
	v_mov_b32_e32 v167, v105
	v_mov_b32_e32 v168, v106
	v_mov_b32_e32 v169, v107
	v_mov_b32_dpp v104, v100 row_shl:8 row_mask:0xf bank_mask:0x3
	v_mov_b32_dpp v105, v101 row_shl:8 row_mask:0xf bank_mask:0x3
	v_mov_b32_dpp v106, v102 row_shl:8 row_mask:0xf bank_mask:0x3
	v_mov_b32_dpp v107, v103 row_shl:8 row_mask:0xf bank_mask:0x3
	v_mov_b32_dpp v100, v166 row_shr:8 row_mask:0xf bank_mask:0xc
	v_mov_b32_dpp v101, v167 row_shr:8 row_mask:0xf bank_mask:0xc
	v_mov_b32_dpp v102, v168 row_shr:8 row_mask:0xf bank_mask:0xc
	v_mov_b32_dpp v103, v169 row_shr:8 row_mask:0xf bank_mask:0xc
	v_mov_b32_e32 v166, v112
	v_mov_b32_e32 v167, v113
	v_mov_b32_e32 v168, v114
	v_mov_b32_e32 v169, v115
	v_mov_b32_dpp v112, v108 row_shl:8 row_mask:0xf bank_mask:0x3
	v_mov_b32_dpp v113, v109 row_shl:8 row_mask:0xf bank_mask:0x3
	v_mov_b32_dpp v114, v110 row_shl:8 row_mask:0xf bank_mask:0x3
	v_mov_b32_dpp v115, v111 row_shl:8 row_mask:0xf bank_mask:0x3
	v_mov_b32_dpp v108, v166 row_shr:8 row_mask:0xf bank_mask:0xc
	v_mov_b32_dpp v109, v167 row_shr:8 row_mask:0xf bank_mask:0xc
	v_mov_b32_dpp v110, v168 row_shr:8 row_mask:0xf bank_mask:0xc
	v_mov_b32_dpp v111, v169 row_shr:8 row_mask:0xf bank_mask:0xc
	v_mov_b32_e32 v166, v120
	v_mov_b32_e32 v167, v121
	v_mov_b32_e32 v168, v122
	v_mov_b32_e32 v169, v123
	v_mov_b32_dpp v120, v116 row_shl:8 row_mask:0xf bank_mask:0x3
	v_mov_b32_dpp v121, v117 row_shl:8 row_mask:0xf bank_mask:0x3
	v_mov_b32_dpp v122, v118 row_shl:8 row_mask:0xf bank_mask:0x3
	v_mov_b32_dpp v123, v119 row_shl:8 row_mask:0xf bank_mask:0x3
	v_mov_b32_dpp v116, v166 row_shr:8 row_mask:0xf bank_mask:0xc
	v_mov_b32_dpp v117, v167 row_shr:8 row_mask:0xf bank_mask:0xc
	v_mov_b32_dpp v118, v168 row_shr:8 row_mask:0xf bank_mask:0xc
	v_mov_b32_dpp v119, v169 row_shr:8 row_mask:0xf bank_mask:0xc
	v_mfma_f32_16x16x32_bf16 v[198:201], v[84:87], v[92:95], v[198:201]
	v_mfma_f32_16x16x32_bf16 v[202:205], v[84:87], v[100:103], v[202:205]
	v_mfma_f32_16x16x32_bf16 v[206:209], v[84:87], v[108:111], v[206:209]
	v_mfma_f32_16x16x32_bf16 v[210:213], v[84:87], v[116:119], v[210:213]
	v_mfma_f32_16x16x32_bf16 v[198:201], v[88:91], v[96:99], v[198:201]
	v_mfma_f32_16x16x32_bf16 v[202:205], v[88:91], v[104:107], v[202:205]
	v_mfma_f32_16x16x32_bf16 v[206:209], v[88:91], v[112:115], v[206:209]
	v_mfma_f32_16x16x32_bf16 v[210:213], v[88:91], v[120:123], v[210:213]
	v_lshl_add_u32 v0, v2, 4, s20
	s_nop 7
	s_nop 7
	ds_write_b128 v0, v[198:201]
	ds_write_b128 v0, v[202:205] offset:1024
	ds_write_b128 v0, v[206:209] offset:2048
	ds_write_b128 v0, v[210:213] offset:3072
	s_cmp_gt_i32 s3, 3
	s_waitcnt lgkmcnt(0)
	s_barrier
	s_cbranch_scc1 .LBB0_1039
	s_lshl_b32 s3, s3, 4
	s_add_i32 s3, s3, s19
	v_bfe_u32 v1, v64, 4, 2
	s_and_b32 s20, s9, -16
	v_or_b32_e32 v0, s3, v63
	v_lshl_or_b32 v4, v1, 2, s20
	v_ashrrev_i32_e32 v1, 31, v0
	v_readlane_b32 s20, v234, 22
	v_lshlrev_b64 v[6:7], 12, v[0:1]
	v_readlane_b32 s21, v234, 23
	v_ashrrev_i32_e32 v5, 31, v4
	s_and_b32 s2, s2, 0xfffffc0
	v_lshl_add_u64 v[6:7], s[20:21], 0, v[6:7]
	v_lshl_add_u64 v[4:5], v[4:5], 1, v[6:7]
	v_add_co_u32_e32 v36, vcc, s8, v4
	s_lshl_b32 s2, s2, 4
	s_nop 0
	v_addc_co_u32_e32 v37, vcc, 0, v5, vcc
	global_load_dwordx2 v[38:39], v[36:37], off
	s_add_i32 s2, s2, 0
	v_and_b32_e32 v4, 64, v62
	v_lshl_add_u32 v32, v2, 4, s2
	v_add_u32_e32 v40, 64, v4
	ds_read_b128 v[4:7], v32
	ds_read_b128 v[8:11], v32 offset:4096
	ds_read_b128 v[12:15], v32 offset:8192
	ds_read_b128 v[16:19], v32 offset:12288
	ds_read_b128 v[20:23], v32 offset:16384
	ds_read_b128 v[24:27], v32 offset:20480
	ds_read_b128 v[28:31], v32 offset:24576
	ds_read_b128 v[32:35], v32 offset:28672
	s_waitcnt lgkmcnt(6)
	v_pk_add_f32 v[6:7], v[6:7], v[10:11]
	v_pk_add_f32 v[4:5], v[4:5], v[8:9]
	s_waitcnt lgkmcnt(5)
	v_pk_add_f32 v[6:7], v[6:7], v[14:15]
	v_pk_add_f32 v[4:5], v[4:5], v[12:13]
	s_waitcnt lgkmcnt(4)
	v_pk_add_f32 v[6:7], v[6:7], v[18:19]
	v_pk_add_f32 v[4:5], v[4:5], v[16:17]
	s_waitcnt lgkmcnt(3)
	v_pk_add_f32 v[6:7], v[6:7], v[22:23]
	v_pk_add_f32 v[4:5], v[4:5], v[20:21]
	s_waitcnt lgkmcnt(2)
	v_pk_add_f32 v[6:7], v[6:7], v[26:27]
	v_pk_add_f32 v[4:5], v[4:5], v[24:25]
	s_waitcnt lgkmcnt(1)
	v_pk_add_f32 v[6:7], v[6:7], v[30:31]
	v_pk_add_f32 v[4:5], v[4:5], v[28:29]
	s_waitcnt lgkmcnt(0)
	v_pk_add_f32 v[6:7], v[6:7], v[34:35]
	v_pk_add_f32 v[4:5], v[4:5], v[32:33]
	v_xor_b32_e32 v3, 16, v62
	v_cmp_lt_i32_e32 vcc, v3, v40
	s_waitcnt vmcnt(0)
	v_lshlrev_b32_e32 v8, 16, v38
	v_and_b32_e32 v9, 0xffff0000, v38
	v_lshlrev_b32_e32 v10, 16, v39
	v_and_b32_e32 v11, 0xffff0000, v39
	v_pk_fma_f32 v[6:7], v[6:7], 0.5, v[10:11] op_sel_hi:[1,0,1]
	v_pk_fma_f32 v[8:9], v[4:5], 0.5, v[8:9] op_sel_hi:[1,0,1]
	v_mul_f32_e32 v5, v7, v7
	v_mul_f32_e32 v4, v9, v9
	v_cndmask_b32_e32 v3, v62, v3, vcc
	v_fmac_f32_e32 v4, v8, v8
	v_fmac_f32_e32 v5, v6, v6
	v_lshlrev_b32_e32 v3, 2, v3
	v_add_f32_e32 v4, v4, v5
	ds_bpermute_b32 v3, v3, v4
	v_xor_b32_e32 v5, 32, v62
	v_cmp_lt_i32_e32 vcc, v5, v40
	v_cvt_pk_bf16_f32 v8, v8, v9
	v_cvt_pk_bf16_f32 v9, v6, v7
	v_cndmask_b32_e32 v5, v62, v5, vcc
	s_waitcnt lgkmcnt(0)
	v_add_f32_e32 v3, v4, v3
	v_lshlrev_b32_e32 v4, 2, v5
	ds_bpermute_b32 v4, v4, v3
	v_cmp_gt_u32_e32 vcc, 16, v2
	global_store_dwordx2 v[36:37], v[8:9], off
	s_and_saveexec_b64 s[2:3], vcc
	s_cbranch_execz .LBB0_1038
	s_waitcnt lgkmcnt(0)
	v_add_f32_e32 v2, v3, v4
	v_mul_f32_e32 v2, 0x4f800000, v2
	v_trunc_f32_e32 v2, v2
	v_mul_f32_e32 v3, 0x2f800000, v2
	v_floor_f32_e32 v3, v3
	v_fmac_f32_e32 v2, 0xcf800000, v3
	v_cvt_u32_f32_e32 v2, v2
	v_cvt_u32_f32_e32 v3, v3
	v_lshl_add_u64 v[0:1], v[0:1], 3, s[0:1]
	global_atomic_add_x2 v[0:1], v[2:3], off
	s_branch .LBB0_1038

.LBB0_2239:
	v_mov_b32_e32 v3, v183
	s_and_b32 s20, s12, 64
	v_readfirstlane_b32 s10, v3
	s_ashr_i32 s11, s10, 6
	v_and_b32_e32 v2, 15, v3
	v_or_b32_e32 v0, s20, v2
	s_lshl_b32 s22, s11, 8
	v_lshlrev_b32_e32 v0, 12, v0
	s_ashr_i32 s23, s22, 31
	v_bfi_b32 v6, 15, v3, s18
	v_lshl_add_u64 v[4:5], s[2:3], 0, v[0:1]
	v_ashrrev_i32_e32 v7, 31, v6
	s_lshl_b64 s[22:23], s[22:23], 1
	v_lshlrev_b64 v[6:7], 12, v[6:7]
	v_lshl_add_u64 v[4:5], v[4:5], 0, s[22:23]
	v_and_b32_e32 v0, 48, v3
	v_lshl_add_u64 v[6:7], s[0:1], 0, v[6:7]
	v_lshl_add_u64 v[28:29], v[4:5], 0, v[0:1]
	v_lshl_add_u64 v[6:7], v[6:7], 0, s[22:23]
	v_lshl_add_u64 v[60:61], v[6:7], 0, v[0:1]
	s_lshl_b32 s21, s11, 12
	v_and_b32_e32 v0, 63, v3
	v_lshrrev_b32_e32 v198, 3, v2
	v_mul_u32_u24_e32 v198, 0x7fc0, v198
	v_sub_u32_e32 v196, 0, v198
	v_ashrrev_i32_e32 v197, 31, v196
	s_mov_b32 s101, 0
	v_lshl_add_u64 v[172:173], v[60:61], 0, v[196:197]
	s_mov_b32 s100, 0x8000
	v_lshl_add_u64 v[174:175], v[172:173], 0, s[100:101]
	v_lshl_add_u64 v[168:169], v[28:29], 0, v[196:197]
	s_mov_b32 s100, 0x2000000
	v_lshl_add_u64 v[176:177], v[168:169], 0, s[100:101]
	s_mov_b32 s100, 0x2008000
	v_lshl_add_u64 v[178:179], v[168:169], 0, s[100:101]
	s_mov_b32 s100, 0x2010000
	v_lshl_add_u64 v[180:181], v[168:169], 0, s[100:101]
	s_mov_b32 s100, 0x2018000
	v_lshl_add_u64 v[184:185], v[168:169], 0, s[100:101]
	s_mov_b32 s100, 0x2020000
	v_lshl_add_u64 v[186:187], v[168:169], 0, s[100:101]
	s_mov_b32 s100, 0x2028000
	v_lshl_add_u64 v[190:191], v[168:169], 0, s[100:101]
	s_mov_b32 s100, 0x2030000
	v_lshl_add_u64 v[192:193], v[168:169], 0, s[100:101]
	s_mov_b32 s100, 0x2038000
	v_lshl_add_u64 v[194:195], v[168:169], 0, s[100:101]
	global_load_dwordx4 v[84:87], v[172:173], off
	global_load_dwordx4 v[88:91], v[174:175], off
	global_load_dwordx4 v[92:95], v[176:177], off
	global_load_dwordx4 v[96:99], v[178:179], off
	global_load_dwordx4 v[100:103], v[180:181], off
	global_load_dwordx4 v[104:107], v[184:185], off
	global_load_dwordx4 v[108:111], v[186:187], off
	global_load_dwordx4 v[112:115], v[190:191], off
	global_load_dwordx4 v[116:119], v[192:193], off
	global_load_dwordx4 v[120:123], v[194:195], off
	global_load_dwordx4 v[124:127], v[172:173], off offset:128
	global_load_dwordx4 v[128:131], v[174:175], off offset:128
	global_load_dwordx4 v[132:135], v[176:177], off offset:128
	global_load_dwordx4 v[136:139], v[178:179], off offset:128
	global_load_dwordx4 v[140:143], v[180:181], off offset:128
	global_load_dwordx4 v[144:147], v[184:185], off offset:128
	global_load_dwordx4 v[152:155], v[186:187], off offset:128
	global_load_dwordx4 v[156:159], v[190:191], off offset:128
	global_load_dwordx4 v[160:163], v[192:193], off offset:128
	global_load_dwordx4 v[164:167], v[194:195], off offset:128
	s_waitcnt vmcnt(10)
	v_mov_b32_e32 v168, v88
	v_mov_b32_e32 v169, v89
	v_mov_b32_e32 v170, v90
	v_mov_b32_e32 v171, v91
	v_mov_b32_dpp v88, v84 row_shl:8 row_mask:0xf bank_mask:0x3
	v_mov_b32_dpp v89, v85 row_shl:8 row_mask:0xf bank_mask:0x3
	v_mov_b32_dpp v90, v86 row_shl:8 row_mask:0xf bank_mask:0x3
	v_mov_b32_dpp v91, v87 row_shl:8 row_mask:0xf bank_mask:0x3
	v_mov_b32_dpp v84, v168 row_shr:8 row_mask:0xf bank_mask:0xc
	v_mov_b32_dpp v85, v169 row_shr:8 row_mask:0xf bank_mask:0xc
	v_mov_b32_dpp v86, v170 row_shr:8 row_mask:0xf bank_mask:0xc
	v_mov_b32_dpp v87, v171 row_shr:8 row_mask:0xf bank_mask:0xc
	v_mov_b32_e32 v168, v96
	v_mov_b32_e32 v169, v97
	v_mov_b32_e32 v170, v98
	v_mov_b32_e32 v171, v99
	v_mov_b32_dpp v96, v92 row_shl:8 row_mask:0xf bank_mask:0x3
	v_mov_b32_dpp v97, v93 row_shl:8 row_mask:0xf bank_mask:0x3
	v_mov_b32_dpp v98, v94 row_shl:8 row_mask:0xf bank_mask:0x3
	v_mov_b32_dpp v99, v95 row_shl:8 row_mask:0xf bank_mask:0x3
	v_mov_b32_dpp v92, v168 row_shr:8 row_mask:0xf bank_mask:0xc
	v_mov_b32_dpp v93, v169 row_shr:8 row_mask:0xf bank_mask:0xc
	v_mov_b32_dpp v94, v170 row_shr:8 row_mask:0xf bank_mask:0xc
	v_mov_b32_dpp v95, v171 row_shr:8 row_mask:0xf bank_mask:0xc
	v_mov_b32_e32 v168, v104
	v_mov_b32_e32 v169, v105
	v_mov_b32_e32 v170, v106
	v_mov_b32_e32 v171, v107
	v_mov_b32_dpp v104, v100 row_shl:8 row_mask:0xf bank_mask:0x3
	v_mov_b32_dpp v105, v101 row_shl:8 row_mask:0xf bank_mask:0x3
	v_mov_b32_dpp v106, v102 row_shl:8 row_mask:0xf bank_mask:0x3
	v_mov_b32_dpp v107, v103 row_shl:8 row_mask:0xf bank_mask:0x3
	v_mov_b32_dpp v100, v168 row_shr:8 row_mask:0xf bank_mask:0xc
	v_mov_b32_dpp v101, v169 row_shr:8 row_mask:0xf bank_mask:0xc
	v_mov_b32_dpp v102, v170 row_shr:8 row_mask:0xf bank_mask:0xc
	v_mov_b32_dpp v103, v171 row_shr:8 row_mask:0xf bank_mask:0xc
	v_mov_b32_e32 v168, v112
	v_mov_b32_e32 v169, v113
	v_mov_b32_e32 v170, v114
	v_mov_b32_e32 v171, v115
	v_mov_b32_dpp v112, v108 row_shl:8 row_mask:0xf bank_mask:0x3
	v_mov_b32_dpp v113, v109 row_shl:8 row_mask:0xf bank_mask:0x3
	v_mov_b32_dpp v114, v110 row_shl:8 row_mask:0xf bank_mask:0x3
	v_mov_b32_dpp v115, v111 row_shl:8 row_mask:0xf bank_mask:0x3
	v_mov_b32_dpp v108, v168 row_shr:8 row_mask:0xf bank_mask:0xc
	v_mov_b32_dpp v109, v169 row_shr:8 row_mask:0xf bank_mask:0xc
	v_mov_b32_dpp v110, v170 row_shr:8 row_mask:0xf bank_mask:0xc
	v_mov_b32_dpp v111, v171 row_shr:8 row_mask:0xf bank_mask:0xc
	v_mov_b32_e32 v168, v120
	v_mov_b32_e32 v169, v121
	v_mov_b32_e32 v170, v122
	v_mov_b32_e32 v171, v123
	v_mov_b32_dpp v120, v116 row_shl:8 row_mask:0xf bank_mask:0x3
	v_mov_b32_dpp v121, v117 row_shl:8 row_mask:0xf bank_mask:0x3
	v_mov_b32_dpp v122, v118 row_shl:8 row_mask:0xf bank_mask:0x3
	v_mov_b32_dpp v123, v119 row_shl:8 row_mask:0xf bank_mask:0x3
	v_mov_b32_dpp v116, v168 row_shr:8 row_mask:0xf bank_mask:0xc
	v_mov_b32_dpp v117, v169 row_shr:8 row_mask:0xf bank_mask:0xc
	v_mov_b32_dpp v118, v170 row_shr:8 row_mask:0xf bank_mask:0xc
	v_mov_b32_dpp v119, v171 row_shr:8 row_mask:0xf bank_mask:0xc
	v_mfma_f32_16x16x32_bf16 v[200:203], v[84:87], v[92:95], 0
	v_mfma_f32_16x16x32_bf16 v[204:207], v[84:87], v[100:103], 0
	v_mfma_f32_16x16x32_bf16 v[208:211], v[84:87], v[108:111], 0
	v_mfma_f32_16x16x32_bf16 v[212:215], v[84:87], v[116:119], 0
	v_mfma_f32_16x16x32_bf16 v[200:203], v[88:91], v[96:99], v[200:203]
	v_mfma_f32_16x16x32_bf16 v[204:207], v[88:91], v[104:107], v[204:207]
	v_mfma_f32_16x16x32_bf16 v[208:211], v[88:91], v[112:115], v[208:211]
	v_mfma_f32_16x16x32_bf16 v[212:215], v[88:91], v[120:123], v[212:215]
	global_load_dwordx4 v[84:87], v[172:173], off offset:256
	global_load_dwordx4 v[88:91], v[174:175], off offset:256
	global_load_dwordx4 v[92:95], v[176:177], off offset:256
	global_load_dwordx4 v[96:99], v[178:179], off offset:256
	global_load_dwordx4 v[100:103], v[180:181], off offset:256
	global_load_dwordx4 v[104:107], v[184:185], off offset:256
	global_load_dwordx4 v[108:111], v[186:187], off offset:256
	global_load_dwordx4 v[112:115], v[190:191], off offset:256
	global_load_dwordx4 v[116:119], v[192:193], off offset:256
	global_load_dwordx4 v[120:123], v[194:195], off offset:256
	s_waitcnt vmcnt(10)
	v_mov_b32_e32 v168, v128
	v_mov_b32_e32 v169, v129
	v_mov_b32_e32 v170, v130
	v_mov_b32_e32 v171, v131
	v_mov_b32_dpp v128, v124 row_shl:8 row_mask:0xf bank_mask:0x3
	v_mov_b32_dpp v129, v125 row_shl:8 row_mask:0xf bank_mask:0x3
	v_mov_b32_dpp v130, v126 row_shl:8 row_mask:0xf bank_mask:0x3
	v_mov_b32_dpp v131, v127 row_shl:8 row_mask:0xf bank_mask:0x3
	v_mov_b32_dpp v124, v168 row_shr:8 row_mask:0xf bank_mask:0xc
	v_mov_b32_dpp v125, v169 row_shr:8 row_mask:0xf bank_mask:0xc
	v_mov_b32_dpp v126, v170 row_shr:8 row_mask:0xf bank_mask:0xc
	v_mov_b32_dpp v127, v171 row_shr:8 row_mask:0xf bank_mask:0xc
	v_mov_b32_e32 v168, v136
	v_mov_b32_e32 v169, v137
	v_mov_b32_e32 v170, v138
	v_mov_b32_e32 v171, v139
	v_mov_b32_dpp v136, v132 row_shl:8 row_mask:0xf bank_mask:0x3
	v_mov_b32_dpp v137, v133 row_shl:8 row_mask:0xf bank_mask:0x3
	v_mov_b32_dpp v138, v134 row_shl:8 row_mask:0xf bank_mask:0x3
	v_mov_b32_dpp v139, v135 row_shl:8 row_mask:0xf bank_mask:0x3
	v_mov_b32_dpp v132, v168 row_shr:8 row_mask:0xf bank_mask:0xc
	v_mov_b32_dpp v133, v169 row_shr:8 row_mask:0xf bank_mask:0xc
	v_mov_b32_dpp v134, v170 row_shr:8 row_mask:0xf bank_mask:0xc
	v_mov_b32_dpp v135, v171 row_shr:8 row_mask:0xf bank_mask:0xc
	v_mov_b32_e32 v168, v144
	v_mov_b32_e32 v169, v145
	v_mov_b32_e32 v170, v146
	v_mov_b32_e32 v171, v147
	v_mov_b32_dpp v144, v140 row_shl:8 row_mask:0xf bank_mask:0x3
	v_mov_b32_dpp v145, v141 row_shl:8 row_mask:0xf bank_mask:0x3
	v_mov_b32_dpp v146, v142 row_shl:8 row_mask:0xf bank_mask:0x3
	v_mov_b32_dpp v147, v143 row_shl:8 row_mask:0xf bank_mask:0x3
	v_mov_b32_dpp v140, v168 row_shr:8 row_mask:0xf bank_mask:0xc
	v_mov_b32_dpp v141, v169 row_shr:8 row_mask:0xf bank_mask:0xc
	v_mov_b32_dpp v142, v170 row_shr:8 row_mask:0xf bank_mask:0xc
	v_mov_b32_dpp v143, v171 row_shr:8 row_mask:0xf bank_mask:0xc
	v_mov_b32_e32 v168, v156
	v_mov_b32_e32 v169, v157
	v_mov_b32_e32 v170, v158
	v_mov_b32_e32 v171, v159
	v_mov_b32_dpp v156, v152 row_shl:8 row_mask:0xf bank_mask:0x3
	v_mov_b32_dpp v157, v153 row_shl:8 row_mask:0xf bank_mask:0x3
	v_mov_b32_dpp v158, v154 row_shl:8 row_mask:0xf bank_mask:0x3
	v_mov_b32_dpp v159, v155 row_shl:8 row_mask:0xf bank_mask:0x3
	v_mov_b32_dpp v152, v168 row_shr:8 row_mask:0xf bank_mask:0xc
	v_mov_b32_dpp v153, v169 row_shr:8 row_mask:0xf bank_mask:0xc
	v_mov_b32_dpp v154, v170 row_shr:8 row_mask:0xf bank_mask:0xc
	v_mov_b32_dpp v155, v171 row_shr:8 row_mask:0xf bank_mask:0xc
	v_mov_b32_e32 v168, v164
	v_mov_b32_e32 v169, v165
	v_mov_b32_e32 v170, v166
	v_mov_b32_e32 v171, v167
	v_mov_b32_dpp v164, v160 row_shl:8 row_mask:0xf bank_mask:0x3
	v_mov_b32_dpp v165, v161 row_shl:8 row_mask:0xf bank_mask:0x3
	v_mov_b32_dpp v166, v162 row_shl:8 row_mask:0xf bank_mask:0x3
	v_mov_b32_dpp v167, v163 row_shl:8 row_mask:0xf bank_mask:0x3
	v_mov_b32_dpp v160, v168 row_shr:8 row_mask:0xf bank_mask:0xc
	v_mov_b32_dpp v161, v169 row_shr:8 row_mask:0xf bank_mask:0xc
	v_mov_b32_dpp v162, v170 row_shr:8 row_mask:0xf bank_mask:0xc
	v_mov_b32_dpp v163, v171 row_shr:8 row_mask:0xf bank_mask:0xc
	v_mfma_f32_16x16x32_bf16 v[200:203], v[124:127], v[132:135], v[200:203]
	v_mfma_f32_16x16x32_bf16 v[204:207], v[124:127], v[140:143], v[204:207]
	v_mfma_f32_16x16x32_bf16 v[208:211], v[124:127], v[152:155], v[208:211]
	v_mfma_f32_16x16x32_bf16 v[212:215], v[124:127], v[160:163], v[212:215]
	v_mfma_f32_16x16x32_bf16 v[200:203], v[128:131], v[136:139], v[200:203]
	v_mfma_f32_16x16x32_bf16 v[204:207], v[128:131], v[144:147], v[204:207]
	v_mfma_f32_16x16x32_bf16 v[208:211], v[128:131], v[156:159], v[208:211]
	v_mfma_f32_16x16x32_bf16 v[212:215], v[128:131], v[164:167], v[212:215]
	global_load_dwordx4 v[124:127], v[172:173], off offset:384
	global_load_dwordx4 v[128:131], v[174:175], off offset:384
	global_load_dwordx4 v[132:135], v[176:177], off offset:384
	global_load_dwordx4 v[136:139], v[178:179], off offset:384
	global_load_dwordx4 v[140:143], v[180:181], off offset:384
	global_load_dwordx4 v[144:147], v[184:185], off offset:384
	global_load_dwordx4 v[152:155], v[186:187], off offset:384
	global_load_dwordx4 v[156:159], v[190:191], off offset:384
	global_load_dwordx4 v[160:163], v[192:193], off offset:384
	global_load_dwordx4 v[164:167], v[194:195], off offset:384
	s_waitcnt vmcnt(10)
	v_mov_b32_e32 v168, v88
	v_mov_b32_e32 v169, v89
	v_mov_b32_e32 v170, v90
	v_mov_b32_e32 v171, v91
	v_mov_b32_dpp v88, v84 row_shl:8 row_mask:0xf bank_mask:0x3
	v_mov_b32_dpp v89, v85 row_shl:8 row_mask:0xf bank_mask:0x3
	v_mov_b32_dpp v90, v86 row_shl:8 row_mask:0xf bank_mask:0x3
	v_mov_b32_dpp v91, v87 row_shl:8 row_mask:0xf bank_mask:0x3
	v_mov_b32_dpp v84, v168 row_shr:8 row_mask:0xf bank_mask:0xc
	v_mov_b32_dpp v85, v169 row_shr:8 row_mask:0xf bank_mask:0xc
	v_mov_b32_dpp v86, v170 row_shr:8 row_mask:0xf bank_mask:0xc
	v_mov_b32_dpp v87, v171 row_shr:8 row_mask:0xf bank_mask:0xc
	v_mov_b32_e32 v168, v96
	v_mov_b32_e32 v169, v97
	v_mov_b32_e32 v170, v98
	v_mov_b32_e32 v171, v99
	v_mov_b32_dpp v96, v92 row_shl:8 row_mask:0xf bank_mask:0x3
	v_mov_b32_dpp v97, v93 row_shl:8 row_mask:0xf bank_mask:0x3
	v_mov_b32_dpp v98, v94 row_shl:8 row_mask:0xf bank_mask:0x3
	v_mov_b32_dpp v99, v95 row_shl:8 row_mask:0xf bank_mask:0x3
	v_mov_b32_dpp v92, v168 row_shr:8 row_mask:0xf bank_mask:0xc
	v_mov_b32_dpp v93, v169 row_shr:8 row_mask:0xf bank_mask:0xc
	v_mov_b32_dpp v94, v170 row_shr:8 row_mask:0xf bank_mask:0xc
	v_mov_b32_dpp v95, v171 row_shr:8 row_mask:0xf bank_mask:0xc
	v_mov_b32_e32 v168, v104
	v_mov_b32_e32 v169, v105
	v_mov_b32_e32 v170, v106
	v_mov_b32_e32 v171, v107
	v_mov_b32_dpp v104, v100 row_shl:8 row_mask:0xf bank_mask:0x3
	v_mov_b32_dpp v105, v101 row_shl:8 row_mask:0xf bank_mask:0x3
	v_mov_b32_dpp v106, v102 row_shl:8 row_mask:0xf bank_mask:0x3
	v_mov_b32_dpp v107, v103 row_shl:8 row_mask:0xf bank_mask:0x3
	v_mov_b32_dpp v100, v168 row_shr:8 row_mask:0xf bank_mask:0xc
	v_mov_b32_dpp v101, v169 row_shr:8 row_mask:0xf bank_mask:0xc
	v_mov_b32_dpp v102, v170 row_shr:8 row_mask:0xf bank_mask:0xc
	v_mov_b32_dpp v103, v171 row_shr:8 row_mask:0xf bank_mask:0xc
	v_mov_b32_e32 v168, v112
	v_mov_b32_e32 v169, v113
	v_mov_b32_e32 v170, v114
	v_mov_b32_e32 v171, v115
	v_mov_b32_dpp v112, v108 row_shl:8 row_mask:0xf bank_mask:0x3
	v_mov_b32_dpp v113, v109 row_shl:8 row_mask:0xf bank_mask:0x3
	v_mov_b32_dpp v114, v110 row_shl:8 row_mask:0xf bank_mask:0x3
	v_mov_b32_dpp v115, v111 row_shl:8 row_mask:0xf bank_mask:0x3
	v_mov_b32_dpp v108, v168 row_shr:8 row_mask:0xf bank_mask:0xc
	v_mov_b32_dpp v109, v169 row_shr:8 row_mask:0xf bank_mask:0xc
	v_mov_b32_dpp v110, v170 row_shr:8 row_mask:0xf bank_mask:0xc
	v_mov_b32_dpp v111, v171 row_shr:8 row_mask:0xf bank_mask:0xc
	v_mov_b32_e32 v168, v120
	v_mov_b32_e32 v169, v121
	v_mov_b32_e32 v170, v122
	v_mov_b32_e32 v171, v123
	v_mov_b32_dpp v120, v116 row_shl:8 row_mask:0xf bank_mask:0x3
	v_mov_b32_dpp v121, v117 row_shl:8 row_mask:0xf bank_mask:0x3
	v_mov_b32_dpp v122, v118 row_shl:8 row_mask:0xf bank_mask:0x3
	v_mov_b32_dpp v123, v119 row_shl:8 row_mask:0xf bank_mask:0x3
	v_mov_b32_dpp v116, v168 row_shr:8 row_mask:0xf bank_mask:0xc
	v_mov_b32_dpp v117, v169 row_shr:8 row_mask:0xf bank_mask:0xc
	v_mov_b32_dpp v118, v170 row_shr:8 row_mask:0xf bank_mask:0xc
	v_mov_b32_dpp v119, v171 row_shr:8 row_mask:0xf bank_mask:0xc
	v_mfma_f32_16x16x32_bf16 v[200:203], v[84:87], v[92:95], v[200:203]
	v_mfma_f32_16x16x32_bf16 v[204:207], v[84:87], v[100:103], v[204:207]
	v_mfma_f32_16x16x32_bf16 v[208:211], v[84:87], v[108:111], v[208:211]
	v_mfma_f32_16x16x32_bf16 v[212:215], v[84:87], v[116:119], v[212:215]
	v_mfma_f32_16x16x32_bf16 v[200:203], v[88:91], v[96:99], v[200:203]
	v_mfma_f32_16x16x32_bf16 v[204:207], v[88:91], v[104:107], v[204:207]
	v_mfma_f32_16x16x32_bf16 v[208:211], v[88:91], v[112:115], v[208:211]
	v_mfma_f32_16x16x32_bf16 v[212:215], v[88:91], v[120:123], v[212:215]
	s_waitcnt vmcnt(0)
	v_mov_b32_e32 v168, v128
	v_mov_b32_e32 v169, v129
	v_mov_b32_e32 v170, v130
	v_mov_b32_e32 v171, v131
	v_mov_b32_dpp v128, v124 row_shl:8 row_mask:0xf bank_mask:0x3
	v_mov_b32_dpp v129, v125 row_shl:8 row_mask:0xf bank_mask:0x3
	v_mov_b32_dpp v130, v126 row_shl:8 row_mask:0xf bank_mask:0x3
	v_mov_b32_dpp v131, v127 row_shl:8 row_mask:0xf bank_mask:0x3
	v_mov_b32_dpp v124, v168 row_shr:8 row_mask:0xf bank_mask:0xc
	v_mov_b32_dpp v125, v169 row_shr:8 row_mask:0xf bank_mask:0xc
	v_mov_b32_dpp v126, v170 row_shr:8 row_mask:0xf bank_mask:0xc
	v_mov_b32_dpp v127, v171 row_shr:8 row_mask:0xf bank_mask:0xc
	v_mov_b32_e32 v168, v136
	v_mov_b32_e32 v169, v137
	v_mov_b32_e32 v170, v138
	v_mov_b32_e32 v171, v139
	v_mov_b32_dpp v136, v132 row_shl:8 row_mask:0xf bank_mask:0x3
	v_mov_b32_dpp v137, v133 row_shl:8 row_mask:0xf bank_mask:0x3
	v_mov_b32_dpp v138, v134 row_shl:8 row_mask:0xf bank_mask:0x3
	v_mov_b32_dpp v139, v135 row_shl:8 row_mask:0xf bank_mask:0x3
	v_mov_b32_dpp v132, v168 row_shr:8 row_mask:0xf bank_mask:0xc
	v_mov_b32_dpp v133, v169 row_shr:8 row_mask:0xf bank_mask:0xc
	v_mov_b32_dpp v134, v170 row_shr:8 row_mask:0xf bank_mask:0xc
	v_mov_b32_dpp v135, v171 row_shr:8 row_mask:0xf bank_mask:0xc
	v_mov_b32_e32 v168, v144
	v_mov_b32_e32 v169, v145
	v_mov_b32_e32 v170, v146
	v_mov_b32_e32 v171, v147
	v_mov_b32_dpp v144, v140 row_shl:8 row_mask:0xf bank_mask:0x3
	v_mov_b32_dpp v145, v141 row_shl:8 row_mask:0xf bank_mask:0x3
	v_mov_b32_dpp v146, v142 row_shl:8 row_mask:0xf bank_mask:0x3
	v_mov_b32_dpp v147, v143 row_shl:8 row_mask:0xf bank_mask:0x3
	v_mov_b32_dpp v140, v168 row_shr:8 row_mask:0xf bank_mask:0xc
	v_mov_b32_dpp v141, v169 row_shr:8 row_mask:0xf bank_mask:0xc
	v_mov_b32_dpp v142, v170 row_shr:8 row_mask:0xf bank_mask:0xc
	v_mov_b32_dpp v143, v171 row_shr:8 row_mask:0xf bank_mask:0xc
	v_mov_b32_e32 v168, v156
	v_mov_b32_e32 v169, v157
	v_mov_b32_e32 v170, v158
	v_mov_b32_e32 v171, v159
	v_mov_b32_dpp v156, v152 row_shl:8 row_mask:0xf bank_mask:0x3
	v_mov_b32_dpp v157, v153 row_shl:8 row_mask:0xf bank_mask:0x3
	v_mov_b32_dpp v158, v154 row_shl:8 row_mask:0xf bank_mask:0x3
	v_mov_b32_dpp v159, v155 row_shl:8 row_mask:0xf bank_mask:0x3
	v_mov_b32_dpp v152, v168 row_shr:8 row_mask:0xf bank_mask:0xc
	v_mov_b32_dpp v153, v169 row_shr:8 row_mask:0xf bank_mask:0xc
	v_mov_b32_dpp v154, v170 row_shr:8 row_mask:0xf bank_mask:0xc
	v_mov_b32_dpp v155, v171 row_shr:8 row_mask:0xf bank_mask:0xc
	v_mov_b32_e32 v168, v164
	v_mov_b32_e32 v169, v165
	v_mov_b32_e32 v170, v166
	v_mov_b32_e32 v171, v167
	v_mov_b32_dpp v164, v160 row_shl:8 row_mask:0xf bank_mask:0x3
	v_mov_b32_dpp v165, v161 row_shl:8 row_mask:0xf bank_mask:0x3
	v_mov_b32_dpp v166, v162 row_shl:8 row_mask:0xf bank_mask:0x3
	v_mov_b32_dpp v167, v163 row_shl:8 row_mask:0xf bank_mask:0x3
	v_mov_b32_dpp v160, v168 row_shr:8 row_mask:0xf bank_mask:0xc
	v_mov_b32_dpp v161, v169 row_shr:8 row_mask:0xf bank_mask:0xc
	v_mov_b32_dpp v162, v170 row_shr:8 row_mask:0xf bank_mask:0xc
	v_mov_b32_dpp v163, v171 row_shr:8 row_mask:0xf bank_mask:0xc
	v_mfma_f32_16x16x32_bf16 v[200:203], v[124:127], v[132:135], v[200:203]
	v_mfma_f32_16x16x32_bf16 v[204:207], v[124:127], v[140:143], v[204:207]
	v_mfma_f32_16x16x32_bf16 v[208:211], v[124:127], v[152:155], v[208:211]
	v_mfma_f32_16x16x32_bf16 v[212:215], v[124:127], v[160:163], v[212:215]
	v_mfma_f32_16x16x32_bf16 v[200:203], v[128:131], v[136:139], v[200:203]
	v_mfma_f32_16x16x32_bf16 v[204:207], v[128:131], v[144:147], v[204:207]
	v_mfma_f32_16x16x32_bf16 v[208:211], v[128:131], v[156:159], v[208:211]
	v_mfma_f32_16x16x32_bf16 v[212:215], v[128:131], v[164:167], v[212:215]
	v_lshl_add_u32 v24, v0, 4, s21
	s_nop 7
	s_nop 7
	ds_write_b128 v24, v[200:203]
	ds_write_b128 v24, v[204:207] offset:1024
	ds_write_b128 v24, v[208:211] offset:2048
	ds_write_b128 v24, v[212:215] offset:3072
	s_cmp_gt_i32 s11, 3
	s_waitcnt lgkmcnt(0)
	s_barrier
	s_cbranch_scc1 .LBB0_2238
	s_lshl_b32 s11, s11, 4
	s_add_i32 s11, s11, s20
	v_bfe_u32 v3, v3, 4, 2
	s_and_b32 s21, s18, -16
	v_or_b32_e32 v2, s11, v2
	v_lshl_or_b32 v4, v3, 2, s21
	v_ashrrev_i32_e32 v3, 31, v2
	v_readlane_b32 s20, v234, 22
	v_lshlrev_b64 v[6:7], 12, v[2:3]
	v_readlane_b32 s21, v234, 23
	v_ashrrev_i32_e32 v5, 31, v4
	s_and_b32 s10, s10, 0xfffffc0
	v_lshl_add_u64 v[6:7], s[20:21], 0, v[6:7]
	v_lshl_add_u64 v[4:5], v[4:5], 1, v[6:7]
	v_add_co_u32_e32 v36, vcc, s14, v4
	s_lshl_b32 s10, s10, 4
	s_nop 0
	v_addc_co_u32_e32 v37, vcc, 0, v5, vcc
	global_load_dwordx2 v[38:39], v[36:37], off
	v_cmp_lt_i32_e32 vcc, v150, v149
	s_add_i32 s10, s10, 0
	v_lshl_add_u32 v32, v0, 4, s10
	v_cndmask_b32_e32 v4, v148, v150, vcc
	v_lshlrev_b32_e32 v40, 2, v4
	ds_read_b128 v[4:7], v32
	ds_read_b128 v[8:11], v32 offset:4096
	ds_read_b128 v[12:15], v32 offset:8192
	ds_read_b128 v[16:19], v32 offset:12288
	ds_read_b128 v[20:23], v32 offset:16384
	ds_read_b128 v[24:27], v32 offset:20480
	ds_read_b128 v[28:31], v32 offset:24576
	ds_read_b128 v[32:35], v32 offset:28672
	s_waitcnt lgkmcnt(6)
	v_pk_add_f32 v[6:7], v[6:7], v[10:11]
	v_pk_add_f32 v[4:5], v[4:5], v[8:9]
	s_waitcnt lgkmcnt(5)
	v_pk_add_f32 v[6:7], v[6:7], v[14:15]
	v_pk_add_f32 v[4:5], v[4:5], v[12:13]
	s_waitcnt lgkmcnt(4)
	v_pk_add_f32 v[6:7], v[6:7], v[18:19]
	v_pk_add_f32 v[4:5], v[4:5], v[16:17]
	s_waitcnt lgkmcnt(3)
	v_pk_add_f32 v[6:7], v[6:7], v[22:23]
	v_pk_add_f32 v[4:5], v[4:5], v[20:21]
	s_waitcnt lgkmcnt(2)
	v_pk_add_f32 v[6:7], v[6:7], v[26:27]
	v_pk_add_f32 v[4:5], v[4:5], v[24:25]
	s_waitcnt lgkmcnt(1)
	v_pk_add_f32 v[6:7], v[6:7], v[30:31]
	v_pk_add_f32 v[4:5], v[4:5], v[28:29]
	s_waitcnt lgkmcnt(0)
	v_pk_add_f32 v[6:7], v[6:7], v[34:35]
	v_pk_add_f32 v[4:5], v[4:5], v[32:33]
	v_cmp_lt_i32_e32 vcc, v151, v149
	s_waitcnt vmcnt(0)
	v_lshlrev_b32_e32 v8, 16, v38
	v_and_b32_e32 v9, 0xffff0000, v38
	v_lshlrev_b32_e32 v10, 16, v39
	v_and_b32_e32 v11, 0xffff0000, v39
	v_pk_add_f32 v[6:7], v[6:7], v[10:11]
	v_pk_add_f32 v[8:9], v[4:5], v[8:9]
	v_mul_f32_e32 v5, v7, v7
	v_mul_f32_e32 v4, v9, v9
	v_fmac_f32_e32 v4, v8, v8
	v_fmac_f32_e32 v5, v6, v6
	v_add_f32_e32 v4, v4, v5
	ds_bpermute_b32 v5, v40, v4
	v_cndmask_b32_e32 v10, v148, v151, vcc
	v_cvt_pk_bf16_f32 v8, v8, v9
	v_cvt_pk_bf16_f32 v9, v6, v7
	v_cmp_gt_u32_e32 vcc, 16, v0
	s_waitcnt lgkmcnt(0)
	v_add_f32_e32 v4, v4, v5
	v_lshlrev_b32_e32 v5, 2, v10
	ds_bpermute_b32 v5, v5, v4
	global_store_dwordx2 v[36:37], v[8:9], off
	s_and_saveexec_b64 s[10:11], vcc
	s_cbranch_execz .LBB0_2237
	s_waitcnt lgkmcnt(0)
	v_add_f32_e32 v0, v4, v5
	v_mul_f32_e32 v0, 0x4f800000, v0
	v_trunc_f32_e32 v0, v0
	v_mul_f32_e32 v4, 0x2f800000, v0
	v_floor_f32_e32 v5, v4
	v_fmac_f32_e32 v0, 0xcf800000, v5
	v_cvt_u32_f32_e32 v4, v0
	v_cvt_u32_f32_e32 v5, v5
	v_lshl_add_u64 v[2:3], v[2:3], 3, s[6:7]
	global_atomic_add_x2 v[2:3], v[4:5], off
	s_branch .LBB0_2237

.LBB0_2420:
	v_mov_b32_e32 v15, v183
	s_and_b32 s15, s6, 64
	v_and_b32_e32 v14, 15, v15
	v_or_b32_e32 v0, s15, v14
	v_readfirstlane_b32 s4, v15
	v_mul_u32_u24_e32 v0, 0x1600, v0
	v_readlane_b32 s16, v233, 8
	s_ashr_i32 s5, s4, 6
	v_lshlrev_b32_e32 v0, 1, v0
	v_readlane_b32 s17, v233, 9
	s_nop 1
	v_lshl_add_u64 v[4:5], s[16:17], 0, v[0:1]
	s_mul_i32 s16, s5, 0x2c0
	s_ashr_i32 s17, s16, 31
	v_bfi_b32 v0, 15, v15, s14
	s_lshl_b64 s[16:17], s[16:17], 1
	v_mad_i64_i32 v[6:7], s[18:19], v0, s8, v[2:3]
	v_lshl_add_u64 v[4:5], v[4:5], 0, s[16:17]
	v_and_b32_e32 v0, 48, v15
	v_lshl_add_u64 v[12:13], v[4:5], 0, v[0:1]
	v_lshl_add_u64 v[6:7], v[6:7], 0, s[16:17]
	v_lshl_add_u64 v[8:9], v[6:7], 0, v[0:1]
	s_lshl_b32 s16, s5, 12
	v_and_b32_e32 v0, 63, v15
	v_lshrrev_b32_e32 v198, 3, v14
	v_mul_u32_u24_e32 v198, 0x15fc0, v198
	v_sub_u32_e32 v196, 0, v198
	v_ashrrev_i32_e32 v197, 31, v196
	s_mov_b32 s101, 0
	v_lshl_add_u64 v[172:173], v[8:9], 0, v[196:197]
	s_mov_b32 s100, 0x16000
	v_lshl_add_u64 v[174:175], v[172:173], 0, s[100:101]
	v_lshl_add_u64 v[168:169], v[12:13], 0, v[196:197]
	s_mov_b32 s100, 0x5800000
	v_lshl_add_u64 v[176:177], v[168:169], 0, s[100:101]
	s_mov_b32 s100, 0x5816000
	v_lshl_add_u64 v[178:179], v[168:169], 0, s[100:101]
	s_mov_b32 s100, 0x582c000
	v_lshl_add_u64 v[180:181], v[168:169], 0, s[100:101]
	s_mov_b32 s100, 0x5842000
	v_lshl_add_u64 v[184:185], v[168:169], 0, s[100:101]
	s_mov_b32 s100, 0x5858000
	v_lshl_add_u64 v[186:187], v[168:169], 0, s[100:101]
	s_mov_b32 s100, 0x586e000
	v_lshl_add_u64 v[190:191], v[168:169], 0, s[100:101]
	s_mov_b32 s100, 0x5884000
	v_lshl_add_u64 v[192:193], v[168:169], 0, s[100:101]
	s_mov_b32 s100, 0x589a000
	v_lshl_add_u64 v[194:195], v[168:169], 0, s[100:101]
	global_load_dwordx4 v[84:87], v[172:173], off
	global_load_dwordx4 v[88:91], v[174:175], off
	global_load_dwordx4 v[92:95], v[176:177], off
	global_load_dwordx4 v[96:99], v[178:179], off
	global_load_dwordx4 v[100:103], v[180:181], off
	global_load_dwordx4 v[104:107], v[184:185], off
	global_load_dwordx4 v[108:111], v[186:187], off
	global_load_dwordx4 v[112:115], v[190:191], off
	global_load_dwordx4 v[116:119], v[192:193], off
	global_load_dwordx4 v[120:123], v[194:195], off
	global_load_dwordx4 v[124:127], v[172:173], off offset:128
	global_load_dwordx4 v[128:131], v[174:175], off offset:128
	global_load_dwordx4 v[132:135], v[176:177], off offset:128
	global_load_dwordx4 v[136:139], v[178:179], off offset:128
	global_load_dwordx4 v[140:143], v[180:181], off offset:128
	global_load_dwordx4 v[144:147], v[184:185], off offset:128
	global_load_dwordx4 v[152:155], v[186:187], off offset:128
	global_load_dwordx4 v[156:159], v[190:191], off offset:128
	global_load_dwordx4 v[160:163], v[192:193], off offset:128
	global_load_dwordx4 v[164:167], v[194:195], off offset:128
	s_waitcnt vmcnt(10)
	v_mov_b32_e32 v168, v88
	v_mov_b32_e32 v169, v89
	v_mov_b32_e32 v170, v90
	v_mov_b32_e32 v171, v91
	v_mov_b32_dpp v88, v84 row_shl:8 row_mask:0xf bank_mask:0x3
	v_mov_b32_dpp v89, v85 row_shl:8 row_mask:0xf bank_mask:0x3
	v_mov_b32_dpp v90, v86 row_shl:8 row_mask:0xf bank_mask:0x3
	v_mov_b32_dpp v91, v87 row_shl:8 row_mask:0xf bank_mask:0x3
	v_mov_b32_dpp v84, v168 row_shr:8 row_mask:0xf bank_mask:0xc
	v_mov_b32_dpp v85, v169 row_shr:8 row_mask:0xf bank_mask:0xc
	v_mov_b32_dpp v86, v170 row_shr:8 row_mask:0xf bank_mask:0xc
	v_mov_b32_dpp v87, v171 row_shr:8 row_mask:0xf bank_mask:0xc
	v_mov_b32_e32 v168, v96
	v_mov_b32_e32 v169, v97
	v_mov_b32_e32 v170, v98
	v_mov_b32_e32 v171, v99
	v_mov_b32_dpp v96, v92 row_shl:8 row_mask:0xf bank_mask:0x3
	v_mov_b32_dpp v97, v93 row_shl:8 row_mask:0xf bank_mask:0x3
	v_mov_b32_dpp v98, v94 row_shl:8 row_mask:0xf bank_mask:0x3
	v_mov_b32_dpp v99, v95 row_shl:8 row_mask:0xf bank_mask:0x3
	v_mov_b32_dpp v92, v168 row_shr:8 row_mask:0xf bank_mask:0xc
	v_mov_b32_dpp v93, v169 row_shr:8 row_mask:0xf bank_mask:0xc
	v_mov_b32_dpp v94, v170 row_shr:8 row_mask:0xf bank_mask:0xc
	v_mov_b32_dpp v95, v171 row_shr:8 row_mask:0xf bank_mask:0xc
	v_mov_b32_e32 v168, v104
	v_mov_b32_e32 v169, v105
	v_mov_b32_e32 v170, v106
	v_mov_b32_e32 v171, v107
	v_mov_b32_dpp v104, v100 row_shl:8 row_mask:0xf bank_mask:0x3
	v_mov_b32_dpp v105, v101 row_shl:8 row_mask:0xf bank_mask:0x3
	v_mov_b32_dpp v106, v102 row_shl:8 row_mask:0xf bank_mask:0x3
	v_mov_b32_dpp v107, v103 row_shl:8 row_mask:0xf bank_mask:0x3
	v_mov_b32_dpp v100, v168 row_shr:8 row_mask:0xf bank_mask:0xc
	v_mov_b32_dpp v101, v169 row_shr:8 row_mask:0xf bank_mask:0xc
	v_mov_b32_dpp v102, v170 row_shr:8 row_mask:0xf bank_mask:0xc
	v_mov_b32_dpp v103, v171 row_shr:8 row_mask:0xf bank_mask:0xc
	v_mov_b32_e32 v168, v112
	v_mov_b32_e32 v169, v113
	v_mov_b32_e32 v170, v114
	v_mov_b32_e32 v171, v115
	v_mov_b32_dpp v112, v108 row_shl:8 row_mask:0xf bank_mask:0x3
	v_mov_b32_dpp v113, v109 row_shl:8 row_mask:0xf bank_mask:0x3
	v_mov_b32_dpp v114, v110 row_shl:8 row_mask:0xf bank_mask:0x3
	v_mov_b32_dpp v115, v111 row_shl:8 row_mask:0xf bank_mask:0x3
	v_mov_b32_dpp v108, v168 row_shr:8 row_mask:0xf bank_mask:0xc
	v_mov_b32_dpp v109, v169 row_shr:8 row_mask:0xf bank_mask:0xc
	v_mov_b32_dpp v110, v170 row_shr:8 row_mask:0xf bank_mask:0xc
	v_mov_b32_dpp v111, v171 row_shr:8 row_mask:0xf bank_mask:0xc
	v_mov_b32_e32 v168, v120
	v_mov_b32_e32 v169, v121
	v_mov_b32_e32 v170, v122
	v_mov_b32_e32 v171, v123
	v_mov_b32_dpp v120, v116 row_shl:8 row_mask:0xf bank_mask:0x3
	v_mov_b32_dpp v121, v117 row_shl:8 row_mask:0xf bank_mask:0x3
	v_mov_b32_dpp v122, v118 row_shl:8 row_mask:0xf bank_mask:0x3
	v_mov_b32_dpp v123, v119 row_shl:8 row_mask:0xf bank_mask:0x3
	v_mov_b32_dpp v116, v168 row_shr:8 row_mask:0xf bank_mask:0xc
	v_mov_b32_dpp v117, v169 row_shr:8 row_mask:0xf bank_mask:0xc
	v_mov_b32_dpp v118, v170 row_shr:8 row_mask:0xf bank_mask:0xc
	v_mov_b32_dpp v119, v171 row_shr:8 row_mask:0xf bank_mask:0xc
	v_mfma_f32_16x16x32_bf16 v[200:203], v[84:87], v[92:95], 0
	v_mfma_f32_16x16x32_bf16 v[204:207], v[84:87], v[100:103], 0
	v_mfma_f32_16x16x32_bf16 v[208:211], v[84:87], v[108:111], 0
	v_mfma_f32_16x16x32_bf16 v[212:215], v[84:87], v[116:119], 0
	v_mfma_f32_16x16x32_bf16 v[200:203], v[88:91], v[96:99], v[200:203]
	v_mfma_f32_16x16x32_bf16 v[204:207], v[88:91], v[104:107], v[204:207]
	v_mfma_f32_16x16x32_bf16 v[208:211], v[88:91], v[112:115], v[208:211]
	v_mfma_f32_16x16x32_bf16 v[212:215], v[88:91], v[120:123], v[212:215]
	global_load_dwordx4 v[84:87], v[172:173], off offset:256
	global_load_dwordx4 v[88:91], v[174:175], off offset:256
	global_load_dwordx4 v[92:95], v[176:177], off offset:256
	global_load_dwordx4 v[96:99], v[178:179], off offset:256
	global_load_dwordx4 v[100:103], v[180:181], off offset:256
	global_load_dwordx4 v[104:107], v[184:185], off offset:256
	global_load_dwordx4 v[108:111], v[186:187], off offset:256
	global_load_dwordx4 v[112:115], v[190:191], off offset:256
	global_load_dwordx4 v[116:119], v[192:193], off offset:256
	global_load_dwordx4 v[120:123], v[194:195], off offset:256
	s_waitcnt vmcnt(10)
	v_mov_b32_e32 v168, v128
	v_mov_b32_e32 v169, v129
	v_mov_b32_e32 v170, v130
	v_mov_b32_e32 v171, v131
	v_mov_b32_dpp v128, v124 row_shl:8 row_mask:0xf bank_mask:0x3
	v_mov_b32_dpp v129, v125 row_shl:8 row_mask:0xf bank_mask:0x3
	v_mov_b32_dpp v130, v126 row_shl:8 row_mask:0xf bank_mask:0x3
	v_mov_b32_dpp v131, v127 row_shl:8 row_mask:0xf bank_mask:0x3
	v_mov_b32_dpp v124, v168 row_shr:8 row_mask:0xf bank_mask:0xc
	v_mov_b32_dpp v125, v169 row_shr:8 row_mask:0xf bank_mask:0xc
	v_mov_b32_dpp v126, v170 row_shr:8 row_mask:0xf bank_mask:0xc
	v_mov_b32_dpp v127, v171 row_shr:8 row_mask:0xf bank_mask:0xc
	v_mov_b32_e32 v168, v136
	v_mov_b32_e32 v169, v137
	v_mov_b32_e32 v170, v138
	v_mov_b32_e32 v171, v139
	v_mov_b32_dpp v136, v132 row_shl:8 row_mask:0xf bank_mask:0x3
	v_mov_b32_dpp v137, v133 row_shl:8 row_mask:0xf bank_mask:0x3
	v_mov_b32_dpp v138, v134 row_shl:8 row_mask:0xf bank_mask:0x3
	v_mov_b32_dpp v139, v135 row_shl:8 row_mask:0xf bank_mask:0x3
	v_mov_b32_dpp v132, v168 row_shr:8 row_mask:0xf bank_mask:0xc
	v_mov_b32_dpp v133, v169 row_shr:8 row_mask:0xf bank_mask:0xc
	v_mov_b32_dpp v134, v170 row_shr:8 row_mask:0xf bank_mask:0xc
	v_mov_b32_dpp v135, v171 row_shr:8 row_mask:0xf bank_mask:0xc
	v_mov_b32_e32 v168, v144
	v_mov_b32_e32 v169, v145
	v_mov_b32_e32 v170, v146
	v_mov_b32_e32 v171, v147
	v_mov_b32_dpp v144, v140 row_shl:8 row_mask:0xf bank_mask:0x3
	v_mov_b32_dpp v145, v141 row_shl:8 row_mask:0xf bank_mask:0x3
	v_mov_b32_dpp v146, v142 row_shl:8 row_mask:0xf bank_mask:0x3
	v_mov_b32_dpp v147, v143 row_shl:8 row_mask:0xf bank_mask:0x3
	v_mov_b32_dpp v140, v168 row_shr:8 row_mask:0xf bank_mask:0xc
	v_mov_b32_dpp v141, v169 row_shr:8 row_mask:0xf bank_mask:0xc
	v_mov_b32_dpp v142, v170 row_shr:8 row_mask:0xf bank_mask:0xc
	v_mov_b32_dpp v143, v171 row_shr:8 row_mask:0xf bank_mask:0xc
	v_mov_b32_e32 v168, v156
	v_mov_b32_e32 v169, v157
	v_mov_b32_e32 v170, v158
	v_mov_b32_e32 v171, v159
	v_mov_b32_dpp v156, v152 row_shl:8 row_mask:0xf bank_mask:0x3
	v_mov_b32_dpp v157, v153 row_shl:8 row_mask:0xf bank_mask:0x3
	v_mov_b32_dpp v158, v154 row_shl:8 row_mask:0xf bank_mask:0x3
	v_mov_b32_dpp v159, v155 row_shl:8 row_mask:0xf bank_mask:0x3
	v_mov_b32_dpp v152, v168 row_shr:8 row_mask:0xf bank_mask:0xc
	v_mov_b32_dpp v153, v169 row_shr:8 row_mask:0xf bank_mask:0xc
	v_mov_b32_dpp v154, v170 row_shr:8 row_mask:0xf bank_mask:0xc
	v_mov_b32_dpp v155, v171 row_shr:8 row_mask:0xf bank_mask:0xc
	v_mov_b32_e32 v168, v164
	v_mov_b32_e32 v169, v165
	v_mov_b32_e32 v170, v166
	v_mov_b32_e32 v171, v167
	v_mov_b32_dpp v164, v160 row_shl:8 row_mask:0xf bank_mask:0x3
	v_mov_b32_dpp v165, v161 row_shl:8 row_mask:0xf bank_mask:0x3
	v_mov_b32_dpp v166, v162 row_shl:8 row_mask:0xf bank_mask:0x3
	v_mov_b32_dpp v167, v163 row_shl:8 row_mask:0xf bank_mask:0x3
	v_mov_b32_dpp v160, v168 row_shr:8 row_mask:0xf bank_mask:0xc
	v_mov_b32_dpp v161, v169 row_shr:8 row_mask:0xf bank_mask:0xc
	v_mov_b32_dpp v162, v170 row_shr:8 row_mask:0xf bank_mask:0xc
	v_mov_b32_dpp v163, v171 row_shr:8 row_mask:0xf bank_mask:0xc
	v_mfma_f32_16x16x32_bf16 v[200:203], v[124:127], v[132:135], v[200:203]
	v_mfma_f32_16x16x32_bf16 v[204:207], v[124:127], v[140:143], v[204:207]
	v_mfma_f32_16x16x32_bf16 v[208:211], v[124:127], v[152:155], v[208:211]
	v_mfma_f32_16x16x32_bf16 v[212:215], v[124:127], v[160:163], v[212:215]
	v_mfma_f32_16x16x32_bf16 v[200:203], v[128:131], v[136:139], v[200:203]
	v_mfma_f32_16x16x32_bf16 v[204:207], v[128:131], v[144:147], v[204:207]
	v_mfma_f32_16x16x32_bf16 v[208:211], v[128:131], v[156:159], v[208:211]
	v_mfma_f32_16x16x32_bf16 v[212:215], v[128:131], v[164:167], v[212:215]
	global_load_dwordx4 v[124:127], v[172:173], off offset:384
	global_load_dwordx4 v[128:131], v[174:175], off offset:384
	global_load_dwordx4 v[132:135], v[176:177], off offset:384
	global_load_dwordx4 v[136:139], v[178:179], off offset:384
	global_load_dwordx4 v[140:143], v[180:181], off offset:384
	global_load_dwordx4 v[144:147], v[184:185], off offset:384
	global_load_dwordx4 v[152:155], v[186:187], off offset:384
	global_load_dwordx4 v[156:159], v[190:191], off offset:384
	global_load_dwordx4 v[160:163], v[192:193], off offset:384
	global_load_dwordx4 v[164:167], v[194:195], off offset:384
	s_waitcnt vmcnt(10)
	v_mov_b32_e32 v168, v88
	v_mov_b32_e32 v169, v89
	v_mov_b32_e32 v170, v90
	v_mov_b32_e32 v171, v91
	v_mov_b32_dpp v88, v84 row_shl:8 row_mask:0xf bank_mask:0x3
	v_mov_b32_dpp v89, v85 row_shl:8 row_mask:0xf bank_mask:0x3
	v_mov_b32_dpp v90, v86 row_shl:8 row_mask:0xf bank_mask:0x3
	v_mov_b32_dpp v91, v87 row_shl:8 row_mask:0xf bank_mask:0x3
	v_mov_b32_dpp v84, v168 row_shr:8 row_mask:0xf bank_mask:0xc
	v_mov_b32_dpp v85, v169 row_shr:8 row_mask:0xf bank_mask:0xc
	v_mov_b32_dpp v86, v170 row_shr:8 row_mask:0xf bank_mask:0xc
	v_mov_b32_dpp v87, v171 row_shr:8 row_mask:0xf bank_mask:0xc
	v_mov_b32_e32 v168, v96
	v_mov_b32_e32 v169, v97
	v_mov_b32_e32 v170, v98
	v_mov_b32_e32 v171, v99
	v_mov_b32_dpp v96, v92 row_shl:8 row_mask:0xf bank_mask:0x3
	v_mov_b32_dpp v97, v93 row_shl:8 row_mask:0xf bank_mask:0x3
	v_mov_b32_dpp v98, v94 row_shl:8 row_mask:0xf bank_mask:0x3
	v_mov_b32_dpp v99, v95 row_shl:8 row_mask:0xf bank_mask:0x3
	v_mov_b32_dpp v92, v168 row_shr:8 row_mask:0xf bank_mask:0xc
	v_mov_b32_dpp v93, v169 row_shr:8 row_mask:0xf bank_mask:0xc
	v_mov_b32_dpp v94, v170 row_shr:8 row_mask:0xf bank_mask:0xc
	v_mov_b32_dpp v95, v171 row_shr:8 row_mask:0xf bank_mask:0xc
	v_mov_b32_e32 v168, v104
	v_mov_b32_e32 v169, v105
	v_mov_b32_e32 v170, v106
	v_mov_b32_e32 v171, v107
	v_mov_b32_dpp v104, v100 row_shl:8 row_mask:0xf bank_mask:0x3
	v_mov_b32_dpp v105, v101 row_shl:8 row_mask:0xf bank_mask:0x3
	v_mov_b32_dpp v106, v102 row_shl:8 row_mask:0xf bank_mask:0x3
	v_mov_b32_dpp v107, v103 row_shl:8 row_mask:0xf bank_mask:0x3
	v_mov_b32_dpp v100, v168 row_shr:8 row_mask:0xf bank_mask:0xc
	v_mov_b32_dpp v101, v169 row_shr:8 row_mask:0xf bank_mask:0xc
	v_mov_b32_dpp v102, v170 row_shr:8 row_mask:0xf bank_mask:0xc
	v_mov_b32_dpp v103, v171 row_shr:8 row_mask:0xf bank_mask:0xc
	v_mov_b32_e32 v168, v112
	v_mov_b32_e32 v169, v113
	v_mov_b32_e32 v170, v114
	v_mov_b32_e32 v171, v115
	v_mov_b32_dpp v112, v108 row_shl:8 row_mask:0xf bank_mask:0x3
	v_mov_b32_dpp v113, v109 row_shl:8 row_mask:0xf bank_mask:0x3
	v_mov_b32_dpp v114, v110 row_shl:8 row_mask:0xf bank_mask:0x3
	v_mov_b32_dpp v115, v111 row_shl:8 row_mask:0xf bank_mask:0x3
	v_mov_b32_dpp v108, v168 row_shr:8 row_mask:0xf bank_mask:0xc
	v_mov_b32_dpp v109, v169 row_shr:8 row_mask:0xf bank_mask:0xc
	v_mov_b32_dpp v110, v170 row_shr:8 row_mask:0xf bank_mask:0xc
	v_mov_b32_dpp v111, v171 row_shr:8 row_mask:0xf bank_mask:0xc
	v_mov_b32_e32 v168, v120
	v_mov_b32_e32 v169, v121
	v_mov_b32_e32 v170, v122
	v_mov_b32_e32 v171, v123
	v_mov_b32_dpp v120, v116 row_shl:8 row_mask:0xf bank_mask:0x3
	v_mov_b32_dpp v121, v117 row_shl:8 row_mask:0xf bank_mask:0x3
	v_mov_b32_dpp v122, v118 row_shl:8 row_mask:0xf bank_mask:0x3
	v_mov_b32_dpp v123, v119 row_shl:8 row_mask:0xf bank_mask:0x3
	v_mov_b32_dpp v116, v168 row_shr:8 row_mask:0xf bank_mask:0xc
	v_mov_b32_dpp v117, v169 row_shr:8 row_mask:0xf bank_mask:0xc
	v_mov_b32_dpp v118, v170 row_shr:8 row_mask:0xf bank_mask:0xc
	v_mov_b32_dpp v119, v171 row_shr:8 row_mask:0xf bank_mask:0xc
	v_mfma_f32_16x16x32_bf16 v[200:203], v[84:87], v[92:95], v[200:203]
	v_mfma_f32_16x16x32_bf16 v[204:207], v[84:87], v[100:103], v[204:207]
	v_mfma_f32_16x16x32_bf16 v[208:211], v[84:87], v[108:111], v[208:211]
	v_mfma_f32_16x16x32_bf16 v[212:215], v[84:87], v[116:119], v[212:215]
	v_mfma_f32_16x16x32_bf16 v[200:203], v[88:91], v[96:99], v[200:203]
	v_mfma_f32_16x16x32_bf16 v[204:207], v[88:91], v[104:107], v[204:207]
	v_mfma_f32_16x16x32_bf16 v[208:211], v[88:91], v[112:115], v[208:211]
	v_mfma_f32_16x16x32_bf16 v[212:215], v[88:91], v[120:123], v[212:215]
	global_load_dwordx4 v[84:87], v[172:173], off offset:512
	global_load_dwordx4 v[88:91], v[174:175], off offset:512
	global_load_dwordx4 v[92:95], v[176:177], off offset:512
	global_load_dwordx4 v[96:99], v[178:179], off offset:512
	global_load_dwordx4 v[100:103], v[180:181], off offset:512
	global_load_dwordx4 v[104:107], v[184:185], off offset:512
	global_load_dwordx4 v[108:111], v[186:187], off offset:512
	global_load_dwordx4 v[112:115], v[190:191], off offset:512
	global_load_dwordx4 v[116:119], v[192:193], off offset:512
	global_load_dwordx4 v[120:123], v[194:195], off offset:512
	s_waitcnt vmcnt(10)
	v_mov_b32_e32 v168, v128
	v_mov_b32_e32 v169, v129
	v_mov_b32_e32 v170, v130
	v_mov_b32_e32 v171, v131
	v_mov_b32_dpp v128, v124 row_shl:8 row_mask:0xf bank_mask:0x3
	v_mov_b32_dpp v129, v125 row_shl:8 row_mask:0xf bank_mask:0x3
	v_mov_b32_dpp v130, v126 row_shl:8 row_mask:0xf bank_mask:0x3
	v_mov_b32_dpp v131, v127 row_shl:8 row_mask:0xf bank_mask:0x3
	v_mov_b32_dpp v124, v168 row_shr:8 row_mask:0xf bank_mask:0xc
	v_mov_b32_dpp v125, v169 row_shr:8 row_mask:0xf bank_mask:0xc
	v_mov_b32_dpp v126, v170 row_shr:8 row_mask:0xf bank_mask:0xc
	v_mov_b32_dpp v127, v171 row_shr:8 row_mask:0xf bank_mask:0xc
	v_mov_b32_e32 v168, v136
	v_mov_b32_e32 v169, v137
	v_mov_b32_e32 v170, v138
	v_mov_b32_e32 v171, v139
	v_mov_b32_dpp v136, v132 row_shl:8 row_mask:0xf bank_mask:0x3
	v_mov_b32_dpp v137, v133 row_shl:8 row_mask:0xf bank_mask:0x3
	v_mov_b32_dpp v138, v134 row_shl:8 row_mask:0xf bank_mask:0x3
	v_mov_b32_dpp v139, v135 row_shl:8 row_mask:0xf bank_mask:0x3
	v_mov_b32_dpp v132, v168 row_shr:8 row_mask:0xf bank_mask:0xc
	v_mov_b32_dpp v133, v169 row_shr:8 row_mask:0xf bank_mask:0xc
	v_mov_b32_dpp v134, v170 row_shr:8 row_mask:0xf bank_mask:0xc
	v_mov_b32_dpp v135, v171 row_shr:8 row_mask:0xf bank_mask:0xc
	v_mov_b32_e32 v168, v144
	v_mov_b32_e32 v169, v145
	v_mov_b32_e32 v170, v146
	v_mov_b32_e32 v171, v147
	v_mov_b32_dpp v144, v140 row_shl:8 row_mask:0xf bank_mask:0x3
	v_mov_b32_dpp v145, v141 row_shl:8 row_mask:0xf bank_mask:0x3
	v_mov_b32_dpp v146, v142 row_shl:8 row_mask:0xf bank_mask:0x3
	v_mov_b32_dpp v147, v143 row_shl:8 row_mask:0xf bank_mask:0x3
	v_mov_b32_dpp v140, v168 row_shr:8 row_mask:0xf bank_mask:0xc
	v_mov_b32_dpp v141, v169 row_shr:8 row_mask:0xf bank_mask:0xc
	v_mov_b32_dpp v142, v170 row_shr:8 row_mask:0xf bank_mask:0xc
	v_mov_b32_dpp v143, v171 row_shr:8 row_mask:0xf bank_mask:0xc
	v_mov_b32_e32 v168, v156
	v_mov_b32_e32 v169, v157
	v_mov_b32_e32 v170, v158
	v_mov_b32_e32 v171, v159
	v_mov_b32_dpp v156, v152 row_shl:8 row_mask:0xf bank_mask:0x3
	v_mov_b32_dpp v157, v153 row_shl:8 row_mask:0xf bank_mask:0x3
	v_mov_b32_dpp v158, v154 row_shl:8 row_mask:0xf bank_mask:0x3
	v_mov_b32_dpp v159, v155 row_shl:8 row_mask:0xf bank_mask:0x3
	v_mov_b32_dpp v152, v168 row_shr:8 row_mask:0xf bank_mask:0xc
	v_mov_b32_dpp v153, v169 row_shr:8 row_mask:0xf bank_mask:0xc
	v_mov_b32_dpp v154, v170 row_shr:8 row_mask:0xf bank_mask:0xc
	v_mov_b32_dpp v155, v171 row_shr:8 row_mask:0xf bank_mask:0xc
	v_mov_b32_e32 v168, v164
	v_mov_b32_e32 v169, v165
	v_mov_b32_e32 v170, v166
	v_mov_b32_e32 v171, v167
	v_mov_b32_dpp v164, v160 row_shl:8 row_mask:0xf bank_mask:0x3
	v_mov_b32_dpp v165, v161 row_shl:8 row_mask:0xf bank_mask:0x3
	v_mov_b32_dpp v166, v162 row_shl:8 row_mask:0xf bank_mask:0x3
	v_mov_b32_dpp v167, v163 row_shl:8 row_mask:0xf bank_mask:0x3
	v_mov_b32_dpp v160, v168 row_shr:8 row_mask:0xf bank_mask:0xc
	v_mov_b32_dpp v161, v169 row_shr:8 row_mask:0xf bank_mask:0xc
	v_mov_b32_dpp v162, v170 row_shr:8 row_mask:0xf bank_mask:0xc
	v_mov_b32_dpp v163, v171 row_shr:8 row_mask:0xf bank_mask:0xc
	v_mfma_f32_16x16x32_bf16 v[200:203], v[124:127], v[132:135], v[200:203]
	v_mfma_f32_16x16x32_bf16 v[204:207], v[124:127], v[140:143], v[204:207]
	v_mfma_f32_16x16x32_bf16 v[208:211], v[124:127], v[152:155], v[208:211]
	v_mfma_f32_16x16x32_bf16 v[212:215], v[124:127], v[160:163], v[212:215]
	v_mfma_f32_16x16x32_bf16 v[200:203], v[128:131], v[136:139], v[200:203]
	v_mfma_f32_16x16x32_bf16 v[204:207], v[128:131], v[144:147], v[204:207]
	v_mfma_f32_16x16x32_bf16 v[208:211], v[128:131], v[156:159], v[208:211]
	v_mfma_f32_16x16x32_bf16 v[212:215], v[128:131], v[164:167], v[212:215]
	global_load_dwordx4 v[124:127], v[172:173], off offset:640
	global_load_dwordx4 v[128:131], v[174:175], off offset:640
	global_load_dwordx4 v[132:135], v[176:177], off offset:640
	global_load_dwordx4 v[136:139], v[178:179], off offset:640
	global_load_dwordx4 v[140:143], v[180:181], off offset:640
	global_load_dwordx4 v[144:147], v[184:185], off offset:640
	global_load_dwordx4 v[152:155], v[186:187], off offset:640
	global_load_dwordx4 v[156:159], v[190:191], off offset:640
	global_load_dwordx4 v[160:163], v[192:193], off offset:640
	global_load_dwordx4 v[164:167], v[194:195], off offset:640
	s_waitcnt vmcnt(10)
	v_mov_b32_e32 v168, v88
	v_mov_b32_e32 v169, v89
	v_mov_b32_e32 v170, v90
	v_mov_b32_e32 v171, v91
	v_mov_b32_dpp v88, v84 row_shl:8 row_mask:0xf bank_mask:0x3
	v_mov_b32_dpp v89, v85 row_shl:8 row_mask:0xf bank_mask:0x3
	v_mov_b32_dpp v90, v86 row_shl:8 row_mask:0xf bank_mask:0x3
	v_mov_b32_dpp v91, v87 row_shl:8 row_mask:0xf bank_mask:0x3
	v_mov_b32_dpp v84, v168 row_shr:8 row_mask:0xf bank_mask:0xc
	v_mov_b32_dpp v85, v169 row_shr:8 row_mask:0xf bank_mask:0xc
	v_mov_b32_dpp v86, v170 row_shr:8 row_mask:0xf bank_mask:0xc
	v_mov_b32_dpp v87, v171 row_shr:8 row_mask:0xf bank_mask:0xc
	v_mov_b32_e32 v168, v96
	v_mov_b32_e32 v169, v97
	v_mov_b32_e32 v170, v98
	v_mov_b32_e32 v171, v99
	v_mov_b32_dpp v96, v92 row_shl:8 row_mask:0xf bank_mask:0x3
	v_mov_b32_dpp v97, v93 row_shl:8 row_mask:0xf bank_mask:0x3
	v_mov_b32_dpp v98, v94 row_shl:8 row_mask:0xf bank_mask:0x3
	v_mov_b32_dpp v99, v95 row_shl:8 row_mask:0xf bank_mask:0x3
	v_mov_b32_dpp v92, v168 row_shr:8 row_mask:0xf bank_mask:0xc
	v_mov_b32_dpp v93, v169 row_shr:8 row_mask:0xf bank_mask:0xc
	v_mov_b32_dpp v94, v170 row_shr:8 row_mask:0xf bank_mask:0xc
	v_mov_b32_dpp v95, v171 row_shr:8 row_mask:0xf bank_mask:0xc
	v_mov_b32_e32 v168, v104
	v_mov_b32_e32 v169, v105
	v_mov_b32_e32 v170, v106
	v_mov_b32_e32 v171, v107
	v_mov_b32_dpp v104, v100 row_shl:8 row_mask:0xf bank_mask:0x3
	v_mov_b32_dpp v105, v101 row_shl:8 row_mask:0xf bank_mask:0x3
	v_mov_b32_dpp v106, v102 row_shl:8 row_mask:0xf bank_mask:0x3
	v_mov_b32_dpp v107, v103 row_shl:8 row_mask:0xf bank_mask:0x3
	v_mov_b32_dpp v100, v168 row_shr:8 row_mask:0xf bank_mask:0xc
	v_mov_b32_dpp v101, v169 row_shr:8 row_mask:0xf bank_mask:0xc
	v_mov_b32_dpp v102, v170 row_shr:8 row_mask:0xf bank_mask:0xc
	v_mov_b32_dpp v103, v171 row_shr:8 row_mask:0xf bank_mask:0xc
	v_mov_b32_e32 v168, v112
	v_mov_b32_e32 v169, v113
	v_mov_b32_e32 v170, v114
	v_mov_b32_e32 v171, v115
	v_mov_b32_dpp v112, v108 row_shl:8 row_mask:0xf bank_mask:0x3
	v_mov_b32_dpp v113, v109 row_shl:8 row_mask:0xf bank_mask:0x3
	v_mov_b32_dpp v114, v110 row_shl:8 row_mask:0xf bank_mask:0x3
	v_mov_b32_dpp v115, v111 row_shl:8 row_mask:0xf bank_mask:0x3
	v_mov_b32_dpp v108, v168 row_shr:8 row_mask:0xf bank_mask:0xc
	v_mov_b32_dpp v109, v169 row_shr:8 row_mask:0xf bank_mask:0xc
	v_mov_b32_dpp v110, v170 row_shr:8 row_mask:0xf bank_mask:0xc
	v_mov_b32_dpp v111, v171 row_shr:8 row_mask:0xf bank_mask:0xc
	v_mov_b32_e32 v168, v120
	v_mov_b32_e32 v169, v121
	v_mov_b32_e32 v170, v122
	v_mov_b32_e32 v171, v123
	v_mov_b32_dpp v120, v116 row_shl:8 row_mask:0xf bank_mask:0x3
	v_mov_b32_dpp v121, v117 row_shl:8 row_mask:0xf bank_mask:0x3
	v_mov_b32_dpp v122, v118 row_shl:8 row_mask:0xf bank_mask:0x3
	v_mov_b32_dpp v123, v119 row_shl:8 row_mask:0xf bank_mask:0x3
	v_mov_b32_dpp v116, v168 row_shr:8 row_mask:0xf bank_mask:0xc
	v_mov_b32_dpp v117, v169 row_shr:8 row_mask:0xf bank_mask:0xc
	v_mov_b32_dpp v118, v170 row_shr:8 row_mask:0xf bank_mask:0xc
	v_mov_b32_dpp v119, v171 row_shr:8 row_mask:0xf bank_mask:0xc
	v_mfma_f32_16x16x32_bf16 v[200:203], v[84:87], v[92:95], v[200:203]
	v_mfma_f32_16x16x32_bf16 v[204:207], v[84:87], v[100:103], v[204:207]
	v_mfma_f32_16x16x32_bf16 v[208:211], v[84:87], v[108:111], v[208:211]
	v_mfma_f32_16x16x32_bf16 v[212:215], v[84:87], v[116:119], v[212:215]
	v_mfma_f32_16x16x32_bf16 v[200:203], v[88:91], v[96:99], v[200:203]
	v_mfma_f32_16x16x32_bf16 v[204:207], v[88:91], v[104:107], v[204:207]
	v_mfma_f32_16x16x32_bf16 v[208:211], v[88:91], v[112:115], v[208:211]
	v_mfma_f32_16x16x32_bf16 v[212:215], v[88:91], v[120:123], v[212:215]
	global_load_dwordx4 v[84:87], v[172:173], off offset:768
	global_load_dwordx4 v[88:91], v[174:175], off offset:768
	global_load_dwordx4 v[92:95], v[176:177], off offset:768
	global_load_dwordx4 v[96:99], v[178:179], off offset:768
	global_load_dwordx4 v[100:103], v[180:181], off offset:768
	global_load_dwordx4 v[104:107], v[184:185], off offset:768
	global_load_dwordx4 v[108:111], v[186:187], off offset:768
	global_load_dwordx4 v[112:115], v[190:191], off offset:768
	global_load_dwordx4 v[116:119], v[192:193], off offset:768
	global_load_dwordx4 v[120:123], v[194:195], off offset:768
	s_waitcnt vmcnt(10)
	v_mov_b32_e32 v168, v128
	v_mov_b32_e32 v169, v129
	v_mov_b32_e32 v170, v130
	v_mov_b32_e32 v171, v131
	v_mov_b32_dpp v128, v124 row_shl:8 row_mask:0xf bank_mask:0x3
	v_mov_b32_dpp v129, v125 row_shl:8 row_mask:0xf bank_mask:0x3
	v_mov_b32_dpp v130, v126 row_shl:8 row_mask:0xf bank_mask:0x3
	v_mov_b32_dpp v131, v127 row_shl:8 row_mask:0xf bank_mask:0x3
	v_mov_b32_dpp v124, v168 row_shr:8 row_mask:0xf bank_mask:0xc
	v_mov_b32_dpp v125, v169 row_shr:8 row_mask:0xf bank_mask:0xc
	v_mov_b32_dpp v126, v170 row_shr:8 row_mask:0xf bank_mask:0xc
	v_mov_b32_dpp v127, v171 row_shr:8 row_mask:0xf bank_mask:0xc
	v_mov_b32_e32 v168, v136
	v_mov_b32_e32 v169, v137
	v_mov_b32_e32 v170, v138
	v_mov_b32_e32 v171, v139
	v_mov_b32_dpp v136, v132 row_shl:8 row_mask:0xf bank_mask:0x3
	v_mov_b32_dpp v137, v133 row_shl:8 row_mask:0xf bank_mask:0x3
	v_mov_b32_dpp v138, v134 row_shl:8 row_mask:0xf bank_mask:0x3
	v_mov_b32_dpp v139, v135 row_shl:8 row_mask:0xf bank_mask:0x3
	v_mov_b32_dpp v132, v168 row_shr:8 row_mask:0xf bank_mask:0xc
	v_mov_b32_dpp v133, v169 row_shr:8 row_mask:0xf bank_mask:0xc
	v_mov_b32_dpp v134, v170 row_shr:8 row_mask:0xf bank_mask:0xc
	v_mov_b32_dpp v135, v171 row_shr:8 row_mask:0xf bank_mask:0xc
	v_mov_b32_e32 v168, v144
	v_mov_b32_e32 v169, v145
	v_mov_b32_e32 v170, v146
	v_mov_b32_e32 v171, v147
	v_mov_b32_dpp v144, v140 row_shl:8 row_mask:0xf bank_mask:0x3
	v_mov_b32_dpp v145, v141 row_shl:8 row_mask:0xf bank_mask:0x3
	v_mov_b32_dpp v146, v142 row_shl:8 row_mask:0xf bank_mask:0x3
	v_mov_b32_dpp v147, v143 row_shl:8 row_mask:0xf bank_mask:0x3
	v_mov_b32_dpp v140, v168 row_shr:8 row_mask:0xf bank_mask:0xc
	v_mov_b32_dpp v141, v169 row_shr:8 row_mask:0xf bank_mask:0xc
	v_mov_b32_dpp v142, v170 row_shr:8 row_mask:0xf bank_mask:0xc
	v_mov_b32_dpp v143, v171 row_shr:8 row_mask:0xf bank_mask:0xc
	v_mov_b32_e32 v168, v156
	v_mov_b32_e32 v169, v157
	v_mov_b32_e32 v170, v158
	v_mov_b32_e32 v171, v159
	v_mov_b32_dpp v156, v152 row_shl:8 row_mask:0xf bank_mask:0x3
	v_mov_b32_dpp v157, v153 row_shl:8 row_mask:0xf bank_mask:0x3
	v_mov_b32_dpp v158, v154 row_shl:8 row_mask:0xf bank_mask:0x3
	v_mov_b32_dpp v159, v155 row_shl:8 row_mask:0xf bank_mask:0x3
	v_mov_b32_dpp v152, v168 row_shr:8 row_mask:0xf bank_mask:0xc
	v_mov_b32_dpp v153, v169 row_shr:8 row_mask:0xf bank_mask:0xc
	v_mov_b32_dpp v154, v170 row_shr:8 row_mask:0xf bank_mask:0xc
	v_mov_b32_dpp v155, v171 row_shr:8 row_mask:0xf bank_mask:0xc
	v_mov_b32_e32 v168, v164
	v_mov_b32_e32 v169, v165
	v_mov_b32_e32 v170, v166
	v_mov_b32_e32 v171, v167
	v_mov_b32_dpp v164, v160 row_shl:8 row_mask:0xf bank_mask:0x3
	v_mov_b32_dpp v165, v161 row_shl:8 row_mask:0xf bank_mask:0x3
	v_mov_b32_dpp v166, v162 row_shl:8 row_mask:0xf bank_mask:0x3
	v_mov_b32_dpp v167, v163 row_shl:8 row_mask:0xf bank_mask:0x3
	v_mov_b32_dpp v160, v168 row_shr:8 row_mask:0xf bank_mask:0xc
	v_mov_b32_dpp v161, v169 row_shr:8 row_mask:0xf bank_mask:0xc
	v_mov_b32_dpp v162, v170 row_shr:8 row_mask:0xf bank_mask:0xc
	v_mov_b32_dpp v163, v171 row_shr:8 row_mask:0xf bank_mask:0xc
	v_mfma_f32_16x16x32_bf16 v[200:203], v[124:127], v[132:135], v[200:203]
	v_mfma_f32_16x16x32_bf16 v[204:207], v[124:127], v[140:143], v[204:207]
	v_mfma_f32_16x16x32_bf16 v[208:211], v[124:127], v[152:155], v[208:211]
	v_mfma_f32_16x16x32_bf16 v[212:215], v[124:127], v[160:163], v[212:215]
	v_mfma_f32_16x16x32_bf16 v[200:203], v[128:131], v[136:139], v[200:203]
	v_mfma_f32_16x16x32_bf16 v[204:207], v[128:131], v[144:147], v[204:207]
	v_mfma_f32_16x16x32_bf16 v[208:211], v[128:131], v[156:159], v[208:211]
	v_mfma_f32_16x16x32_bf16 v[212:215], v[128:131], v[164:167], v[212:215]
	global_load_dwordx4 v[124:127], v[172:173], off offset:896
	global_load_dwordx4 v[128:131], v[174:175], off offset:896
	global_load_dwordx4 v[132:135], v[176:177], off offset:896
	global_load_dwordx4 v[136:139], v[178:179], off offset:896
	global_load_dwordx4 v[140:143], v[180:181], off offset:896
	global_load_dwordx4 v[144:147], v[184:185], off offset:896
	global_load_dwordx4 v[152:155], v[186:187], off offset:896
	global_load_dwordx4 v[156:159], v[190:191], off offset:896
	global_load_dwordx4 v[160:163], v[192:193], off offset:896
	global_load_dwordx4 v[164:167], v[194:195], off offset:896
	s_waitcnt vmcnt(10)
	v_mov_b32_e32 v168, v88
	v_mov_b32_e32 v169, v89
	v_mov_b32_e32 v170, v90
	v_mov_b32_e32 v171, v91
	v_mov_b32_dpp v88, v84 row_shl:8 row_mask:0xf bank_mask:0x3
	v_mov_b32_dpp v89, v85 row_shl:8 row_mask:0xf bank_mask:0x3
	v_mov_b32_dpp v90, v86 row_shl:8 row_mask:0xf bank_mask:0x3
	v_mov_b32_dpp v91, v87 row_shl:8 row_mask:0xf bank_mask:0x3
	v_mov_b32_dpp v84, v168 row_shr:8 row_mask:0xf bank_mask:0xc
	v_mov_b32_dpp v85, v169 row_shr:8 row_mask:0xf bank_mask:0xc
	v_mov_b32_dpp v86, v170 row_shr:8 row_mask:0xf bank_mask:0xc
	v_mov_b32_dpp v87, v171 row_shr:8 row_mask:0xf bank_mask:0xc
	v_mov_b32_e32 v168, v96
	v_mov_b32_e32 v169, v97
	v_mov_b32_e32 v170, v98
	v_mov_b32_e32 v171, v99
	v_mov_b32_dpp v96, v92 row_shl:8 row_mask:0xf bank_mask:0x3
	v_mov_b32_dpp v97, v93 row_shl:8 row_mask:0xf bank_mask:0x3
	v_mov_b32_dpp v98, v94 row_shl:8 row_mask:0xf bank_mask:0x3
	v_mov_b32_dpp v99, v95 row_shl:8 row_mask:0xf bank_mask:0x3
	v_mov_b32_dpp v92, v168 row_shr:8 row_mask:0xf bank_mask:0xc
	v_mov_b32_dpp v93, v169 row_shr:8 row_mask:0xf bank_mask:0xc
	v_mov_b32_dpp v94, v170 row_shr:8 row_mask:0xf bank_mask:0xc
	v_mov_b32_dpp v95, v171 row_shr:8 row_mask:0xf bank_mask:0xc
	v_mov_b32_e32 v168, v104
	v_mov_b32_e32 v169, v105
	v_mov_b32_e32 v170, v106
	v_mov_b32_e32 v171, v107
	v_mov_b32_dpp v104, v100 row_shl:8 row_mask:0xf bank_mask:0x3
	v_mov_b32_dpp v105, v101 row_shl:8 row_mask:0xf bank_mask:0x3
	v_mov_b32_dpp v106, v102 row_shl:8 row_mask:0xf bank_mask:0x3
	v_mov_b32_dpp v107, v103 row_shl:8 row_mask:0xf bank_mask:0x3
	v_mov_b32_dpp v100, v168 row_shr:8 row_mask:0xf bank_mask:0xc
	v_mov_b32_dpp v101, v169 row_shr:8 row_mask:0xf bank_mask:0xc
	v_mov_b32_dpp v102, v170 row_shr:8 row_mask:0xf bank_mask:0xc
	v_mov_b32_dpp v103, v171 row_shr:8 row_mask:0xf bank_mask:0xc
	v_mov_b32_e32 v168, v112
	v_mov_b32_e32 v169, v113
	v_mov_b32_e32 v170, v114
	v_mov_b32_e32 v171, v115
	v_mov_b32_dpp v112, v108 row_shl:8 row_mask:0xf bank_mask:0x3
	v_mov_b32_dpp v113, v109 row_shl:8 row_mask:0xf bank_mask:0x3
	v_mov_b32_dpp v114, v110 row_shl:8 row_mask:0xf bank_mask:0x3
	v_mov_b32_dpp v115, v111 row_shl:8 row_mask:0xf bank_mask:0x3
	v_mov_b32_dpp v108, v168 row_shr:8 row_mask:0xf bank_mask:0xc
	v_mov_b32_dpp v109, v169 row_shr:8 row_mask:0xf bank_mask:0xc
	v_mov_b32_dpp v110, v170 row_shr:8 row_mask:0xf bank_mask:0xc
	v_mov_b32_dpp v111, v171 row_shr:8 row_mask:0xf bank_mask:0xc
	v_mov_b32_e32 v168, v120
	v_mov_b32_e32 v169, v121
	v_mov_b32_e32 v170, v122
	v_mov_b32_e32 v171, v123
	v_mov_b32_dpp v120, v116 row_shl:8 row_mask:0xf bank_mask:0x3
	v_mov_b32_dpp v121, v117 row_shl:8 row_mask:0xf bank_mask:0x3
	v_mov_b32_dpp v122, v118 row_shl:8 row_mask:0xf bank_mask:0x3
	v_mov_b32_dpp v123, v119 row_shl:8 row_mask:0xf bank_mask:0x3
	v_mov_b32_dpp v116, v168 row_shr:8 row_mask:0xf bank_mask:0xc
	v_mov_b32_dpp v117, v169 row_shr:8 row_mask:0xf bank_mask:0xc
	v_mov_b32_dpp v118, v170 row_shr:8 row_mask:0xf bank_mask:0xc
	v_mov_b32_dpp v119, v171 row_shr:8 row_mask:0xf bank_mask:0xc
	v_mfma_f32_16x16x32_bf16 v[200:203], v[84:87], v[92:95], v[200:203]
	v_mfma_f32_16x16x32_bf16 v[204:207], v[84:87], v[100:103], v[204:207]
	v_mfma_f32_16x16x32_bf16 v[208:211], v[84:87], v[108:111], v[208:211]
	v_mfma_f32_16x16x32_bf16 v[212:215], v[84:87], v[116:119], v[212:215]
	v_mfma_f32_16x16x32_bf16 v[200:203], v[88:91], v[96:99], v[200:203]
	v_mfma_f32_16x16x32_bf16 v[204:207], v[88:91], v[104:107], v[204:207]
	v_mfma_f32_16x16x32_bf16 v[208:211], v[88:91], v[112:115], v[208:211]
	v_mfma_f32_16x16x32_bf16 v[212:215], v[88:91], v[120:123], v[212:215]
	global_load_dwordx4 v[84:87], v[172:173], off offset:1024
	global_load_dwordx4 v[88:91], v[174:175], off offset:1024
	global_load_dwordx4 v[92:95], v[176:177], off offset:1024
	global_load_dwordx4 v[96:99], v[178:179], off offset:1024
	global_load_dwordx4 v[100:103], v[180:181], off offset:1024
	global_load_dwordx4 v[104:107], v[184:185], off offset:1024
	global_load_dwordx4 v[108:111], v[186:187], off offset:1024
	global_load_dwordx4 v[112:115], v[190:191], off offset:1024
	global_load_dwordx4 v[116:119], v[192:193], off offset:1024
	global_load_dwordx4 v[120:123], v[194:195], off offset:1024
	s_waitcnt vmcnt(10)
	v_mov_b32_e32 v168, v128
	v_mov_b32_e32 v169, v129
	v_mov_b32_e32 v170, v130
	v_mov_b32_e32 v171, v131
	v_mov_b32_dpp v128, v124 row_shl:8 row_mask:0xf bank_mask:0x3
	v_mov_b32_dpp v129, v125 row_shl:8 row_mask:0xf bank_mask:0x3
	v_mov_b32_dpp v130, v126 row_shl:8 row_mask:0xf bank_mask:0x3
	v_mov_b32_dpp v131, v127 row_shl:8 row_mask:0xf bank_mask:0x3
	v_mov_b32_dpp v124, v168 row_shr:8 row_mask:0xf bank_mask:0xc
	v_mov_b32_dpp v125, v169 row_shr:8 row_mask:0xf bank_mask:0xc
	v_mov_b32_dpp v126, v170 row_shr:8 row_mask:0xf bank_mask:0xc
	v_mov_b32_dpp v127, v171 row_shr:8 row_mask:0xf bank_mask:0xc
	v_mov_b32_e32 v168, v136
	v_mov_b32_e32 v169, v137
	v_mov_b32_e32 v170, v138
	v_mov_b32_e32 v171, v139
	v_mov_b32_dpp v136, v132 row_shl:8 row_mask:0xf bank_mask:0x3
	v_mov_b32_dpp v137, v133 row_shl:8 row_mask:0xf bank_mask:0x3
	v_mov_b32_dpp v138, v134 row_shl:8 row_mask:0xf bank_mask:0x3
	v_mov_b32_dpp v139, v135 row_shl:8 row_mask:0xf bank_mask:0x3
	v_mov_b32_dpp v132, v168 row_shr:8 row_mask:0xf bank_mask:0xc
	v_mov_b32_dpp v133, v169 row_shr:8 row_mask:0xf bank_mask:0xc
	v_mov_b32_dpp v134, v170 row_shr:8 row_mask:0xf bank_mask:0xc
	v_mov_b32_dpp v135, v171 row_shr:8 row_mask:0xf bank_mask:0xc
	v_mov_b32_e32 v168, v144
	v_mov_b32_e32 v169, v145
	v_mov_b32_e32 v170, v146
	v_mov_b32_e32 v171, v147
	v_mov_b32_dpp v144, v140 row_shl:8 row_mask:0xf bank_mask:0x3
	v_mov_b32_dpp v145, v141 row_shl:8 row_mask:0xf bank_mask:0x3
	v_mov_b32_dpp v146, v142 row_shl:8 row_mask:0xf bank_mask:0x3
	v_mov_b32_dpp v147, v143 row_shl:8 row_mask:0xf bank_mask:0x3
	v_mov_b32_dpp v140, v168 row_shr:8 row_mask:0xf bank_mask:0xc
	v_mov_b32_dpp v141, v169 row_shr:8 row_mask:0xf bank_mask:0xc
	v_mov_b32_dpp v142, v170 row_shr:8 row_mask:0xf bank_mask:0xc
	v_mov_b32_dpp v143, v171 row_shr:8 row_mask:0xf bank_mask:0xc
	v_mov_b32_e32 v168, v156
	v_mov_b32_e32 v169, v157
	v_mov_b32_e32 v170, v158
	v_mov_b32_e32 v171, v159
	v_mov_b32_dpp v156, v152 row_shl:8 row_mask:0xf bank_mask:0x3
	v_mov_b32_dpp v157, v153 row_shl:8 row_mask:0xf bank_mask:0x3
	v_mov_b32_dpp v158, v154 row_shl:8 row_mask:0xf bank_mask:0x3
	v_mov_b32_dpp v159, v155 row_shl:8 row_mask:0xf bank_mask:0x3
	v_mov_b32_dpp v152, v168 row_shr:8 row_mask:0xf bank_mask:0xc
	v_mov_b32_dpp v153, v169 row_shr:8 row_mask:0xf bank_mask:0xc
	v_mov_b32_dpp v154, v170 row_shr:8 row_mask:0xf bank_mask:0xc
	v_mov_b32_dpp v155, v171 row_shr:8 row_mask:0xf bank_mask:0xc
	v_mov_b32_e32 v168, v164
	v_mov_b32_e32 v169, v165
	v_mov_b32_e32 v170, v166
	v_mov_b32_e32 v171, v167
	v_mov_b32_dpp v164, v160 row_shl:8 row_mask:0xf bank_mask:0x3
	v_mov_b32_dpp v165, v161 row_shl:8 row_mask:0xf bank_mask:0x3
	v_mov_b32_dpp v166, v162 row_shl:8 row_mask:0xf bank_mask:0x3
	v_mov_b32_dpp v167, v163 row_shl:8 row_mask:0xf bank_mask:0x3
	v_mov_b32_dpp v160, v168 row_shr:8 row_mask:0xf bank_mask:0xc
	v_mov_b32_dpp v161, v169 row_shr:8 row_mask:0xf bank_mask:0xc
	v_mov_b32_dpp v162, v170 row_shr:8 row_mask:0xf bank_mask:0xc
	v_mov_b32_dpp v163, v171 row_shr:8 row_mask:0xf bank_mask:0xc
	v_mfma_f32_16x16x32_bf16 v[200:203], v[124:127], v[132:135], v[200:203]
	v_mfma_f32_16x16x32_bf16 v[204:207], v[124:127], v[140:143], v[204:207]
	v_mfma_f32_16x16x32_bf16 v[208:211], v[124:127], v[152:155], v[208:211]
	v_mfma_f32_16x16x32_bf16 v[212:215], v[124:127], v[160:163], v[212:215]
	v_mfma_f32_16x16x32_bf16 v[200:203], v[128:131], v[136:139], v[200:203]
	v_mfma_f32_16x16x32_bf16 v[204:207], v[128:131], v[144:147], v[204:207]
	v_mfma_f32_16x16x32_bf16 v[208:211], v[128:131], v[156:159], v[208:211]
	v_mfma_f32_16x16x32_bf16 v[212:215], v[128:131], v[164:167], v[212:215]
	global_load_dwordx4 v[124:127], v[172:173], off offset:1152
	global_load_dwordx4 v[128:131], v[174:175], off offset:1152
	global_load_dwordx4 v[132:135], v[176:177], off offset:1152
	global_load_dwordx4 v[136:139], v[178:179], off offset:1152
	global_load_dwordx4 v[140:143], v[180:181], off offset:1152
	global_load_dwordx4 v[144:147], v[184:185], off offset:1152
	global_load_dwordx4 v[152:155], v[186:187], off offset:1152
	global_load_dwordx4 v[156:159], v[190:191], off offset:1152
	global_load_dwordx4 v[160:163], v[192:193], off offset:1152
	global_load_dwordx4 v[164:167], v[194:195], off offset:1152
	s_waitcnt vmcnt(10)
	v_mov_b32_e32 v168, v88
	v_mov_b32_e32 v169, v89
	v_mov_b32_e32 v170, v90
	v_mov_b32_e32 v171, v91
	v_mov_b32_dpp v88, v84 row_shl:8 row_mask:0xf bank_mask:0x3
	v_mov_b32_dpp v89, v85 row_shl:8 row_mask:0xf bank_mask:0x3
	v_mov_b32_dpp v90, v86 row_shl:8 row_mask:0xf bank_mask:0x3
	v_mov_b32_dpp v91, v87 row_shl:8 row_mask:0xf bank_mask:0x3
	v_mov_b32_dpp v84, v168 row_shr:8 row_mask:0xf bank_mask:0xc
	v_mov_b32_dpp v85, v169 row_shr:8 row_mask:0xf bank_mask:0xc
	v_mov_b32_dpp v86, v170 row_shr:8 row_mask:0xf bank_mask:0xc
	v_mov_b32_dpp v87, v171 row_shr:8 row_mask:0xf bank_mask:0xc
	v_mov_b32_e32 v168, v96
	v_mov_b32_e32 v169, v97
	v_mov_b32_e32 v170, v98
	v_mov_b32_e32 v171, v99
	v_mov_b32_dpp v96, v92 row_shl:8 row_mask:0xf bank_mask:0x3
	v_mov_b32_dpp v97, v93 row_shl:8 row_mask:0xf bank_mask:0x3
	v_mov_b32_dpp v98, v94 row_shl:8 row_mask:0xf bank_mask:0x3
	v_mov_b32_dpp v99, v95 row_shl:8 row_mask:0xf bank_mask:0x3
	v_mov_b32_dpp v92, v168 row_shr:8 row_mask:0xf bank_mask:0xc
	v_mov_b32_dpp v93, v169 row_shr:8 row_mask:0xf bank_mask:0xc
	v_mov_b32_dpp v94, v170 row_shr:8 row_mask:0xf bank_mask:0xc
	v_mov_b32_dpp v95, v171 row_shr:8 row_mask:0xf bank_mask:0xc
	v_mov_b32_e32 v168, v104
	v_mov_b32_e32 v169, v105
	v_mov_b32_e32 v170, v106
	v_mov_b32_e32 v171, v107
	v_mov_b32_dpp v104, v100 row_shl:8 row_mask:0xf bank_mask:0x3
	v_mov_b32_dpp v105, v101 row_shl:8 row_mask:0xf bank_mask:0x3
	v_mov_b32_dpp v106, v102 row_shl:8 row_mask:0xf bank_mask:0x3
	v_mov_b32_dpp v107, v103 row_shl:8 row_mask:0xf bank_mask:0x3
	v_mov_b32_dpp v100, v168 row_shr:8 row_mask:0xf bank_mask:0xc
	v_mov_b32_dpp v101, v169 row_shr:8 row_mask:0xf bank_mask:0xc
	v_mov_b32_dpp v102, v170 row_shr:8 row_mask:0xf bank_mask:0xc
	v_mov_b32_dpp v103, v171 row_shr:8 row_mask:0xf bank_mask:0xc
	v_mov_b32_e32 v168, v112
	v_mov_b32_e32 v169, v113
	v_mov_b32_e32 v170, v114
	v_mov_b32_e32 v171, v115
	v_mov_b32_dpp v112, v108 row_shl:8 row_mask:0xf bank_mask:0x3
	v_mov_b32_dpp v113, v109 row_shl:8 row_mask:0xf bank_mask:0x3
	v_mov_b32_dpp v114, v110 row_shl:8 row_mask:0xf bank_mask:0x3
	v_mov_b32_dpp v115, v111 row_shl:8 row_mask:0xf bank_mask:0x3
	v_mov_b32_dpp v108, v168 row_shr:8 row_mask:0xf bank_mask:0xc
	v_mov_b32_dpp v109, v169 row_shr:8 row_mask:0xf bank_mask:0xc
	v_mov_b32_dpp v110, v170 row_shr:8 row_mask:0xf bank_mask:0xc
	v_mov_b32_dpp v111, v171 row_shr:8 row_mask:0xf bank_mask:0xc
	v_mov_b32_e32 v168, v120
	v_mov_b32_e32 v169, v121
	v_mov_b32_e32 v170, v122
	v_mov_b32_e32 v171, v123
	v_mov_b32_dpp v120, v116 row_shl:8 row_mask:0xf bank_mask:0x3
	v_mov_b32_dpp v121, v117 row_shl:8 row_mask:0xf bank_mask:0x3
	v_mov_b32_dpp v122, v118 row_shl:8 row_mask:0xf bank_mask:0x3
	v_mov_b32_dpp v123, v119 row_shl:8 row_mask:0xf bank_mask:0x3
	v_mov_b32_dpp v116, v168 row_shr:8 row_mask:0xf bank_mask:0xc
	v_mov_b32_dpp v117, v169 row_shr:8 row_mask:0xf bank_mask:0xc
	v_mov_b32_dpp v118, v170 row_shr:8 row_mask:0xf bank_mask:0xc
	v_mov_b32_dpp v119, v171 row_shr:8 row_mask:0xf bank_mask:0xc
	v_mfma_f32_16x16x32_bf16 v[200:203], v[84:87], v[92:95], v[200:203]
	v_mfma_f32_16x16x32_bf16 v[204:207], v[84:87], v[100:103], v[204:207]
	v_mfma_f32_16x16x32_bf16 v[208:211], v[84:87], v[108:111], v[208:211]
	v_mfma_f32_16x16x32_bf16 v[212:215], v[84:87], v[116:119], v[212:215]
	v_mfma_f32_16x16x32_bf16 v[200:203], v[88:91], v[96:99], v[200:203]
	v_mfma_f32_16x16x32_bf16 v[204:207], v[88:91], v[104:107], v[204:207]
	v_mfma_f32_16x16x32_bf16 v[208:211], v[88:91], v[112:115], v[208:211]
	v_mfma_f32_16x16x32_bf16 v[212:215], v[88:91], v[120:123], v[212:215]
	global_load_dwordx4 v[84:87], v[172:173], off offset:1280
	global_load_dwordx4 v[88:91], v[174:175], off offset:1280
	global_load_dwordx4 v[92:95], v[176:177], off offset:1280
	global_load_dwordx4 v[96:99], v[178:179], off offset:1280
	global_load_dwordx4 v[100:103], v[180:181], off offset:1280
	global_load_dwordx4 v[104:107], v[184:185], off offset:1280
	global_load_dwordx4 v[108:111], v[186:187], off offset:1280
	global_load_dwordx4 v[112:115], v[190:191], off offset:1280
	global_load_dwordx4 v[116:119], v[192:193], off offset:1280
	global_load_dwordx4 v[120:123], v[194:195], off offset:1280
	s_waitcnt vmcnt(10)
	v_mov_b32_e32 v168, v128
	v_mov_b32_e32 v169, v129
	v_mov_b32_e32 v170, v130
	v_mov_b32_e32 v171, v131
	v_mov_b32_dpp v128, v124 row_shl:8 row_mask:0xf bank_mask:0x3
	v_mov_b32_dpp v129, v125 row_shl:8 row_mask:0xf bank_mask:0x3
	v_mov_b32_dpp v130, v126 row_shl:8 row_mask:0xf bank_mask:0x3
	v_mov_b32_dpp v131, v127 row_shl:8 row_mask:0xf bank_mask:0x3
	v_mov_b32_dpp v124, v168 row_shr:8 row_mask:0xf bank_mask:0xc
	v_mov_b32_dpp v125, v169 row_shr:8 row_mask:0xf bank_mask:0xc
	v_mov_b32_dpp v126, v170 row_shr:8 row_mask:0xf bank_mask:0xc
	v_mov_b32_dpp v127, v171 row_shr:8 row_mask:0xf bank_mask:0xc
	v_mov_b32_e32 v168, v136
	v_mov_b32_e32 v169, v137
	v_mov_b32_e32 v170, v138
	v_mov_b32_e32 v171, v139
	v_mov_b32_dpp v136, v132 row_shl:8 row_mask:0xf bank_mask:0x3
	v_mov_b32_dpp v137, v133 row_shl:8 row_mask:0xf bank_mask:0x3
	v_mov_b32_dpp v138, v134 row_shl:8 row_mask:0xf bank_mask:0x3
	v_mov_b32_dpp v139, v135 row_shl:8 row_mask:0xf bank_mask:0x3
	v_mov_b32_dpp v132, v168 row_shr:8 row_mask:0xf bank_mask:0xc
	v_mov_b32_dpp v133, v169 row_shr:8 row_mask:0xf bank_mask:0xc
	v_mov_b32_dpp v134, v170 row_shr:8 row_mask:0xf bank_mask:0xc
	v_mov_b32_dpp v135, v171 row_shr:8 row_mask:0xf bank_mask:0xc
	v_mov_b32_e32 v168, v144
	v_mov_b32_e32 v169, v145
	v_mov_b32_e32 v170, v146
	v_mov_b32_e32 v171, v147
	v_mov_b32_dpp v144, v140 row_shl:8 row_mask:0xf bank_mask:0x3
	v_mov_b32_dpp v145, v141 row_shl:8 row_mask:0xf bank_mask:0x3
	v_mov_b32_dpp v146, v142 row_shl:8 row_mask:0xf bank_mask:0x3
	v_mov_b32_dpp v147, v143 row_shl:8 row_mask:0xf bank_mask:0x3
	v_mov_b32_dpp v140, v168 row_shr:8 row_mask:0xf bank_mask:0xc
	v_mov_b32_dpp v141, v169 row_shr:8 row_mask:0xf bank_mask:0xc
	v_mov_b32_dpp v142, v170 row_shr:8 row_mask:0xf bank_mask:0xc
	v_mov_b32_dpp v143, v171 row_shr:8 row_mask:0xf bank_mask:0xc
	v_mov_b32_e32 v168, v156
	v_mov_b32_e32 v169, v157
	v_mov_b32_e32 v170, v158
	v_mov_b32_e32 v171, v159
	v_mov_b32_dpp v156, v152 row_shl:8 row_mask:0xf bank_mask:0x3
	v_mov_b32_dpp v157, v153 row_shl:8 row_mask:0xf bank_mask:0x3
	v_mov_b32_dpp v158, v154 row_shl:8 row_mask:0xf bank_mask:0x3
	v_mov_b32_dpp v159, v155 row_shl:8 row_mask:0xf bank_mask:0x3
	v_mov_b32_dpp v152, v168 row_shr:8 row_mask:0xf bank_mask:0xc
	v_mov_b32_dpp v153, v169 row_shr:8 row_mask:0xf bank_mask:0xc
	v_mov_b32_dpp v154, v170 row_shr:8 row_mask:0xf bank_mask:0xc
	v_mov_b32_dpp v155, v171 row_shr:8 row_mask:0xf bank_mask:0xc
	v_mov_b32_e32 v168, v164
	v_mov_b32_e32 v169, v165
	v_mov_b32_e32 v170, v166
	v_mov_b32_e32 v171, v167
	v_mov_b32_dpp v164, v160 row_shl:8 row_mask:0xf bank_mask:0x3
	v_mov_b32_dpp v165, v161 row_shl:8 row_mask:0xf bank_mask:0x3
	v_mov_b32_dpp v166, v162 row_shl:8 row_mask:0xf bank_mask:0x3
	v_mov_b32_dpp v167, v163 row_shl:8 row_mask:0xf bank_mask:0x3
	v_mov_b32_dpp v160, v168 row_shr:8 row_mask:0xf bank_mask:0xc
	v_mov_b32_dpp v161, v169 row_shr:8 row_mask:0xf bank_mask:0xc
	v_mov_b32_dpp v162, v170 row_shr:8 row_mask:0xf bank_mask:0xc
	v_mov_b32_dpp v163, v171 row_shr:8 row_mask:0xf bank_mask:0xc
	v_mfma_f32_16x16x32_bf16 v[200:203], v[124:127], v[132:135], v[200:203]
	v_mfma_f32_16x16x32_bf16 v[204:207], v[124:127], v[140:143], v[204:207]
	v_mfma_f32_16x16x32_bf16 v[208:211], v[124:127], v[152:155], v[208:211]
	v_mfma_f32_16x16x32_bf16 v[212:215], v[124:127], v[160:163], v[212:215]
	v_mfma_f32_16x16x32_bf16 v[200:203], v[128:131], v[136:139], v[200:203]
	v_mfma_f32_16x16x32_bf16 v[204:207], v[128:131], v[144:147], v[204:207]
	v_mfma_f32_16x16x32_bf16 v[208:211], v[128:131], v[156:159], v[208:211]
	v_mfma_f32_16x16x32_bf16 v[212:215], v[128:131], v[164:167], v[212:215]
	s_waitcnt vmcnt(0)
	v_mov_b32_e32 v168, v88
	v_mov_b32_e32 v169, v89
	v_mov_b32_e32 v170, v90
	v_mov_b32_e32 v171, v91
	v_mov_b32_dpp v88, v84 row_shl:8 row_mask:0xf bank_mask:0x3
	v_mov_b32_dpp v89, v85 row_shl:8 row_mask:0xf bank_mask:0x3
	v_mov_b32_dpp v90, v86 row_shl:8 row_mask:0xf bank_mask:0x3
	v_mov_b32_dpp v91, v87 row_shl:8 row_mask:0xf bank_mask:0x3
	v_mov_b32_dpp v84, v168 row_shr:8 row_mask:0xf bank_mask:0xc
	v_mov_b32_dpp v85, v169 row_shr:8 row_mask:0xf bank_mask:0xc
	v_mov_b32_dpp v86, v170 row_shr:8 row_mask:0xf bank_mask:0xc
	v_mov_b32_dpp v87, v171 row_shr:8 row_mask:0xf bank_mask:0xc
	v_mov_b32_e32 v168, v96
	v_mov_b32_e32 v169, v97
	v_mov_b32_e32 v170, v98
	v_mov_b32_e32 v171, v99
	v_mov_b32_dpp v96, v92 row_shl:8 row_mask:0xf bank_mask:0x3
	v_mov_b32_dpp v97, v93 row_shl:8 row_mask:0xf bank_mask:0x3
	v_mov_b32_dpp v98, v94 row_shl:8 row_mask:0xf bank_mask:0x3
	v_mov_b32_dpp v99, v95 row_shl:8 row_mask:0xf bank_mask:0x3
	v_mov_b32_dpp v92, v168 row_shr:8 row_mask:0xf bank_mask:0xc
	v_mov_b32_dpp v93, v169 row_shr:8 row_mask:0xf bank_mask:0xc
	v_mov_b32_dpp v94, v170 row_shr:8 row_mask:0xf bank_mask:0xc
	v_mov_b32_dpp v95, v171 row_shr:8 row_mask:0xf bank_mask:0xc
	v_mov_b32_e32 v168, v104
	v_mov_b32_e32 v169, v105
	v_mov_b32_e32 v170, v106
	v_mov_b32_e32 v171, v107
	v_mov_b32_dpp v104, v100 row_shl:8 row_mask:0xf bank_mask:0x3
	v_mov_b32_dpp v105, v101 row_shl:8 row_mask:0xf bank_mask:0x3
	v_mov_b32_dpp v106, v102 row_shl:8 row_mask:0xf bank_mask:0x3
	v_mov_b32_dpp v107, v103 row_shl:8 row_mask:0xf bank_mask:0x3
	v_mov_b32_dpp v100, v168 row_shr:8 row_mask:0xf bank_mask:0xc
	v_mov_b32_dpp v101, v169 row_shr:8 row_mask:0xf bank_mask:0xc
	v_mov_b32_dpp v102, v170 row_shr:8 row_mask:0xf bank_mask:0xc
	v_mov_b32_dpp v103, v171 row_shr:8 row_mask:0xf bank_mask:0xc
	v_mov_b32_e32 v168, v112
	v_mov_b32_e32 v169, v113
	v_mov_b32_e32 v170, v114
	v_mov_b32_e32 v171, v115
	v_mov_b32_dpp v112, v108 row_shl:8 row_mask:0xf bank_mask:0x3
	v_mov_b32_dpp v113, v109 row_shl:8 row_mask:0xf bank_mask:0x3
	v_mov_b32_dpp v114, v110 row_shl:8 row_mask:0xf bank_mask:0x3
	v_mov_b32_dpp v115, v111 row_shl:8 row_mask:0xf bank_mask:0x3
	v_mov_b32_dpp v108, v168 row_shr:8 row_mask:0xf bank_mask:0xc
	v_mov_b32_dpp v109, v169 row_shr:8 row_mask:0xf bank_mask:0xc
	v_mov_b32_dpp v110, v170 row_shr:8 row_mask:0xf bank_mask:0xc
	v_mov_b32_dpp v111, v171 row_shr:8 row_mask:0xf bank_mask:0xc
	v_mov_b32_e32 v168, v120
	v_mov_b32_e32 v169, v121
	v_mov_b32_e32 v170, v122
	v_mov_b32_e32 v171, v123
	v_mov_b32_dpp v120, v116 row_shl:8 row_mask:0xf bank_mask:0x3
	v_mov_b32_dpp v121, v117 row_shl:8 row_mask:0xf bank_mask:0x3
	v_mov_b32_dpp v122, v118 row_shl:8 row_mask:0xf bank_mask:0x3
	v_mov_b32_dpp v123, v119 row_shl:8 row_mask:0xf bank_mask:0x3
	v_mov_b32_dpp v116, v168 row_shr:8 row_mask:0xf bank_mask:0xc
	v_mov_b32_dpp v117, v169 row_shr:8 row_mask:0xf bank_mask:0xc
	v_mov_b32_dpp v118, v170 row_shr:8 row_mask:0xf bank_mask:0xc
	v_mov_b32_dpp v119, v171 row_shr:8 row_mask:0xf bank_mask:0xc
	v_mfma_f32_16x16x32_bf16 v[200:203], v[84:87], v[92:95], v[200:203]
	v_mfma_f32_16x16x32_bf16 v[204:207], v[84:87], v[100:103], v[204:207]
	v_mfma_f32_16x16x32_bf16 v[208:211], v[84:87], v[108:111], v[208:211]
	v_mfma_f32_16x16x32_bf16 v[212:215], v[84:87], v[116:119], v[212:215]
	v_mfma_f32_16x16x32_bf16 v[200:203], v[88:91], v[96:99], v[200:203]
	v_mfma_f32_16x16x32_bf16 v[204:207], v[88:91], v[104:107], v[204:207]
	v_mfma_f32_16x16x32_bf16 v[208:211], v[88:91], v[112:115], v[208:211]
	v_mfma_f32_16x16x32_bf16 v[212:215], v[88:91], v[120:123], v[212:215]
	v_lshl_add_u32 v12, v0, 4, s16
	s_nop 7
	s_nop 7
	ds_write_b128 v12, v[200:203]
	ds_write_b128 v12, v[204:207] offset:1024
	ds_write_b128 v12, v[208:211] offset:2048
	ds_write_b128 v12, v[212:215] offset:3072
	s_cmp_gt_i32 s5, 3
	s_waitcnt lgkmcnt(0)
	s_barrier
	s_cbranch_scc1 .LBB0_2419
	s_lshl_b32 s5, s5, 4
	s_add_i32 s5, s5, s15
	v_bfe_u32 v5, v15, 4, 2
	s_and_b32 s16, s14, -16
	v_or_b32_e32 v4, s5, v14
	v_lshl_or_b32 v6, v5, 2, s16
	v_ashrrev_i32_e32 v5, 31, v4
	v_readlane_b32 s16, v234, 22
	v_lshlrev_b64 v[8:9], 12, v[4:5]
	v_readlane_b32 s17, v234, 23
	v_ashrrev_i32_e32 v7, 31, v6
	s_and_b32 s4, s4, 0xfffffc0
	v_lshl_add_u64 v[8:9], s[16:17], 0, v[8:9]
	v_lshl_add_u64 v[6:7], v[6:7], 1, v[8:9]
	v_add_co_u32_e32 v38, vcc, s13, v6
	s_lshl_b32 s4, s4, 4
	s_nop 0
	v_addc_co_u32_e32 v39, vcc, 0, v7, vcc
	global_load_dwordx2 v[40:41], v[38:39], off
	v_cmp_lt_i32_e32 vcc, v150, v149
	s_add_i32 s4, s4, 0
	v_lshl_add_u32 v34, v0, 4, s4
	v_cndmask_b32_e32 v6, v148, v150, vcc
	v_lshlrev_b32_e32 v42, 2, v6
	ds_read_b128 v[6:9], v34
	ds_read_b128 v[10:13], v34 offset:4096
	ds_read_b128 v[14:17], v34 offset:8192
	ds_read_b128 v[18:21], v34 offset:12288
	ds_read_b128 v[22:25], v34 offset:16384
	ds_read_b128 v[26:29], v34 offset:20480
	ds_read_b128 v[30:33], v34 offset:24576
	ds_read_b128 v[34:37], v34 offset:28672
	s_waitcnt lgkmcnt(6)
	v_pk_add_f32 v[8:9], v[8:9], v[12:13]
	v_pk_add_f32 v[6:7], v[6:7], v[10:11]
	s_waitcnt lgkmcnt(5)
	v_pk_add_f32 v[8:9], v[8:9], v[16:17]
	v_pk_add_f32 v[6:7], v[6:7], v[14:15]
	s_waitcnt lgkmcnt(4)
	v_pk_add_f32 v[8:9], v[8:9], v[20:21]
	v_pk_add_f32 v[6:7], v[6:7], v[18:19]
	s_waitcnt lgkmcnt(3)
	v_pk_add_f32 v[8:9], v[8:9], v[24:25]
	v_pk_add_f32 v[6:7], v[6:7], v[22:23]
	s_waitcnt lgkmcnt(2)
	v_pk_add_f32 v[8:9], v[8:9], v[28:29]
	v_pk_add_f32 v[6:7], v[6:7], v[26:27]
	s_waitcnt lgkmcnt(1)
	v_pk_add_f32 v[8:9], v[8:9], v[32:33]
	v_pk_add_f32 v[6:7], v[6:7], v[30:31]
	s_waitcnt lgkmcnt(0)
	v_pk_add_f32 v[8:9], v[8:9], v[36:37]
	v_pk_add_f32 v[6:7], v[6:7], v[34:35]
	v_cmp_lt_i32_e32 vcc, v151, v149
	s_waitcnt vmcnt(0)
	v_lshlrev_b32_e32 v10, 16, v40
	v_and_b32_e32 v11, 0xffff0000, v40
	v_lshlrev_b32_e32 v12, 16, v41
	v_and_b32_e32 v13, 0xffff0000, v41
	v_pk_fma_f32 v[8:9], v[8:9], 0.5, v[12:13] op_sel_hi:[1,0,1]
	v_pk_fma_f32 v[10:11], v[6:7], 0.5, v[10:11] op_sel_hi:[1,0,1]
	v_mul_f32_e32 v7, v9, v9
	v_mul_f32_e32 v6, v11, v11
	v_fmac_f32_e32 v6, v10, v10
	v_fmac_f32_e32 v7, v8, v8
	v_add_f32_e32 v6, v6, v7
	ds_bpermute_b32 v7, v42, v6
	v_cndmask_b32_e32 v12, v148, v151, vcc
	v_cvt_pk_bf16_f32 v10, v10, v11
	v_cvt_pk_bf16_f32 v11, v8, v9
	v_cmp_gt_u32_e32 vcc, 16, v0
	s_waitcnt lgkmcnt(0)
	v_add_f32_e32 v6, v6, v7
	v_lshlrev_b32_e32 v7, 2, v12
	ds_bpermute_b32 v7, v7, v6
	global_store_dwordx2 v[38:39], v[10:11], off
	s_and_saveexec_b64 s[4:5], vcc
	s_cbranch_execz .LBB0_2418
	s_waitcnt lgkmcnt(0)
	v_add_f32_e32 v0, v6, v7
	v_mul_f32_e32 v0, 0x4f800000, v0
	v_trunc_f32_e32 v0, v0
	v_mul_f32_e32 v6, 0x2f800000, v0
	v_floor_f32_e32 v7, v6
	v_fmac_f32_e32 v0, 0xcf800000, v7
	v_cvt_u32_f32_e32 v6, v0
	v_cvt_u32_f32_e32 v7, v7
	v_lshl_add_u64 v[4:5], v[4:5], 3, s[0:1]
	global_atomic_add_x2 v[4:5], v[6:7], off
	s_branch .LBB0_2418
